# sigmoid+bias GEMM epilogue: bias quads loaded once per tile, stores no longer gate the next load (same sigmoid arithmetic)
# speedup vs baseline: 1.0586x; 1.0026x over previous
.LBB0_398:
	s_and_b64 vcc, exec, s[2:3]
	s_cbranch_vccz .LBB0_400
	v_lshl_add_u32 v142, s44, 8, v29
	v_lshl_or_b32 v144, s63, 8, v179
	v_ashrrev_i32_e32 v145, 31, v144
	v_lshlrev_b64 v[144:145], 2, v[144:145]
	v_lshl_add_u64 v[174:175], v[132:133], 0, v[144:145]
	global_load_dwordx4 v[210:213], v[174:175], off
	global_load_dwordx4 v[214:217], v[174:175], off offset:64
	global_load_dwordx4 v[218:221], v[174:175], off offset:512
	global_load_dwordx4 v[222:225], v[174:175], off offset:576
	v_mad_i64_i32 v[180:181], s[2:3], v164, v142, 0
	v_lshl_add_u64 v[180:181], v[180:181], 2, v[130:131]
	v_lshl_add_u64 v[180:181], v[180:181], 0, v[144:145]
	v_or_b32_e32 v143, 16, v142
	v_mad_i64_i32 v[182:183], s[2:3], v164, v143, 0
	v_lshl_add_u64 v[182:183], v[182:183], 2, v[130:131]
	v_lshl_add_u64 v[182:183], v[182:183], 0, v[144:145]
	v_or_b32_e32 v143, 32, v142
	v_mad_i64_i32 v[184:185], s[2:3], v164, v143, 0
	v_lshl_add_u64 v[184:185], v[184:185], 2, v[130:131]
	v_lshl_add_u64 v[184:185], v[184:185], 0, v[144:145]
	v_or_b32_e32 v143, 48, v142
	v_mad_i64_i32 v[186:187], s[2:3], v164, v143, 0
	v_lshl_add_u64 v[186:187], v[186:187], 2, v[130:131]
	v_lshl_add_u64 v[186:187], v[186:187], 0, v[144:145]
	v_or_b32_e32 v143, 0x80, v142
	v_mad_i64_i32 v[188:189], s[2:3], v164, v143, 0
	v_lshl_add_u64 v[188:189], v[188:189], 2, v[130:131]
	v_lshl_add_u64 v[188:189], v[188:189], 0, v[144:145]
	v_or_b32_e32 v143, 0x90, v142
	v_mad_i64_i32 v[190:191], s[2:3], v164, v143, 0
	v_lshl_add_u64 v[190:191], v[190:191], 2, v[130:131]
	v_lshl_add_u64 v[190:191], v[190:191], 0, v[144:145]
	v_or_b32_e32 v143, 0xa0, v142
	v_mad_i64_i32 v[192:193], s[2:3], v164, v143, 0
	v_lshl_add_u64 v[192:193], v[192:193], 2, v[130:131]
	v_lshl_add_u64 v[192:193], v[192:193], 0, v[144:145]
	v_or_b32_e32 v143, 0xb0, v142
	v_mad_i64_i32 v[194:195], s[2:3], v164, v143, 0
	v_lshl_add_u64 v[194:195], v[194:195], 2, v[130:131]
	v_lshl_add_u64 v[194:195], v[194:195], 0, v[144:145]
	s_waitcnt vmcnt(0)
	v_add_f32_e32 v226, v114, v210
	v_add_f32_e32 v227, v115, v211
	v_add_f32_e32 v228, v116, v212
	v_add_f32_e32 v229, v117, v213
	v_mul_f32_e32 v226, 0xbfb8aa3b, v226
	v_mul_f32_e32 v227, 0xbfb8aa3b, v227
	v_mul_f32_e32 v228, 0xbfb8aa3b, v228
	v_mul_f32_e32 v229, 0xbfb8aa3b, v229
	v_exp_f32_e32 v226, v226
	v_exp_f32_e32 v227, v227
	v_exp_f32_e32 v228, v228
	v_exp_f32_e32 v229, v229
	v_add_f32_e32 v226, 1.0, v226
	v_add_f32_e32 v227, 1.0, v227
	v_add_f32_e32 v228, 1.0, v228
	v_add_f32_e32 v229, 1.0, v229
	v_div_scale_f32 v134, s[2:3], v226, v226, 1.0
	v_div_scale_f32 v139, s[2:3], v227, v227, 1.0
	v_rcp_f32_e32 v135, v134
	v_rcp_f32_e32 v140, v139
	v_fma_f32 v136, -v134, v135, 1.0
	v_fma_f32 v141, -v139, v140, 1.0
	v_fmac_f32_e32 v135, v136, v135
	v_fmac_f32_e32 v140, v141, v140
	v_div_scale_f32 v137, vcc, 1.0, v226, 1.0
	v_mul_f32_e32 v138, v137, v135
	v_fma_f32 v136, -v134, v138, v137
	v_fmac_f32_e32 v138, v136, v135
	v_fma_f32 v134, -v134, v138, v137
	v_div_fmas_f32 v134, v134, v135, v138
	v_div_fixup_f32 v226, v134, v226, 1.0
	v_div_scale_f32 v165, vcc, 1.0, v227, 1.0
	v_mul_f32_e32 v166, v165, v140
	v_fma_f32 v141, -v139, v166, v165
	v_fmac_f32_e32 v166, v141, v140
	v_fma_f32 v139, -v139, v166, v165
	v_div_fmas_f32 v139, v139, v140, v166
	v_div_fixup_f32 v227, v139, v227, 1.0
	v_div_scale_f32 v134, s[2:3], v228, v228, 1.0
	v_div_scale_f32 v139, s[2:3], v229, v229, 1.0
	v_rcp_f32_e32 v135, v134
	v_rcp_f32_e32 v140, v139
	v_fma_f32 v136, -v134, v135, 1.0
	v_fma_f32 v141, -v139, v140, 1.0
	v_fmac_f32_e32 v135, v136, v135
	v_fmac_f32_e32 v140, v141, v140
	v_div_scale_f32 v137, vcc, 1.0, v228, 1.0
	v_mul_f32_e32 v138, v137, v135
	v_fma_f32 v136, -v134, v138, v137
	v_fmac_f32_e32 v138, v136, v135
	v_fma_f32 v134, -v134, v138, v137
	v_div_fmas_f32 v134, v134, v135, v138
	v_div_fixup_f32 v228, v134, v228, 1.0
	v_div_scale_f32 v165, vcc, 1.0, v229, 1.0
	v_mul_f32_e32 v166, v165, v140
	v_fma_f32 v141, -v139, v166, v165
	v_fmac_f32_e32 v166, v141, v140
	v_fma_f32 v139, -v139, v166, v165
	v_div_fmas_f32 v139, v139, v140, v166
	v_div_fixup_f32 v229, v139, v229, 1.0
	global_store_dwordx4 v[180:181], v[226:229], off
	v_add_f32_e32 v230, v126, v214
	v_add_f32_e32 v231, v127, v215
	v_add_f32_e32 v232, v128, v216
	v_add_f32_e32 v233, v129, v217
	v_mul_f32_e32 v230, 0xbfb8aa3b, v230
	v_mul_f32_e32 v231, 0xbfb8aa3b, v231
	v_mul_f32_e32 v232, 0xbfb8aa3b, v232
	v_mul_f32_e32 v233, 0xbfb8aa3b, v233
	v_exp_f32_e32 v230, v230
	v_exp_f32_e32 v231, v231
	v_exp_f32_e32 v232, v232
	v_exp_f32_e32 v233, v233
	v_add_f32_e32 v230, 1.0, v230
	v_add_f32_e32 v231, 1.0, v231
	v_add_f32_e32 v232, 1.0, v232
	v_add_f32_e32 v233, 1.0, v233
	v_div_scale_f32 v134, s[2:3], v230, v230, 1.0
	v_div_scale_f32 v139, s[2:3], v231, v231, 1.0
	v_rcp_f32_e32 v135, v134
	v_rcp_f32_e32 v140, v139
	v_fma_f32 v136, -v134, v135, 1.0
	v_fma_f32 v141, -v139, v140, 1.0
	v_fmac_f32_e32 v135, v136, v135
	v_fmac_f32_e32 v140, v141, v140
	v_div_scale_f32 v137, vcc, 1.0, v230, 1.0
	v_mul_f32_e32 v138, v137, v135
	v_fma_f32 v136, -v134, v138, v137
	v_fmac_f32_e32 v138, v136, v135
	v_fma_f32 v134, -v134, v138, v137
	v_div_fmas_f32 v134, v134, v135, v138
	v_div_fixup_f32 v230, v134, v230, 1.0
	v_div_scale_f32 v165, vcc, 1.0, v231, 1.0
	v_mul_f32_e32 v166, v165, v140
	v_fma_f32 v141, -v139, v166, v165
	v_fmac_f32_e32 v166, v141, v140
	v_fma_f32 v139, -v139, v166, v165
	v_div_fmas_f32 v139, v139, v140, v166
	v_div_fixup_f32 v231, v139, v231, 1.0
	v_div_scale_f32 v134, s[2:3], v232, v232, 1.0
	v_div_scale_f32 v139, s[2:3], v233, v233, 1.0
	v_rcp_f32_e32 v135, v134
	v_rcp_f32_e32 v140, v139
	v_fma_f32 v136, -v134, v135, 1.0
	v_fma_f32 v141, -v139, v140, 1.0
	v_fmac_f32_e32 v135, v136, v135
	v_fmac_f32_e32 v140, v141, v140
	v_div_scale_f32 v137, vcc, 1.0, v232, 1.0
	v_mul_f32_e32 v138, v137, v135
	v_fma_f32 v136, -v134, v138, v137
	v_fmac_f32_e32 v138, v136, v135
	v_fma_f32 v134, -v134, v138, v137
	v_div_fmas_f32 v134, v134, v135, v138
	v_div_fixup_f32 v232, v134, v232, 1.0
	v_div_scale_f32 v165, vcc, 1.0, v233, 1.0
	v_mul_f32_e32 v166, v165, v140
	v_fma_f32 v141, -v139, v166, v165
	v_fmac_f32_e32 v166, v141, v140
	v_fma_f32 v139, -v139, v166, v165
	v_div_fmas_f32 v139, v139, v140, v166
	v_div_fixup_f32 v233, v139, v233, 1.0
	global_store_dwordx4 v[180:181], v[230:233], off offset:64
	v_add_f32_e32 v226, v122, v218
	v_add_f32_e32 v227, v123, v219
	v_add_f32_e32 v228, v124, v220
	v_add_f32_e32 v229, v125, v221
	v_mul_f32_e32 v226, 0xbfb8aa3b, v226
	v_mul_f32_e32 v227, 0xbfb8aa3b, v227
	v_mul_f32_e32 v228, 0xbfb8aa3b, v228
	v_mul_f32_e32 v229, 0xbfb8aa3b, v229
	v_exp_f32_e32 v226, v226
	v_exp_f32_e32 v227, v227
	v_exp_f32_e32 v228, v228
	v_exp_f32_e32 v229, v229
	v_add_f32_e32 v226, 1.0, v226
	v_add_f32_e32 v227, 1.0, v227
	v_add_f32_e32 v228, 1.0, v228
	v_add_f32_e32 v229, 1.0, v229
	v_div_scale_f32 v134, s[2:3], v226, v226, 1.0
	v_div_scale_f32 v139, s[2:3], v227, v227, 1.0
	v_rcp_f32_e32 v135, v134
	v_rcp_f32_e32 v140, v139
	v_fma_f32 v136, -v134, v135, 1.0
	v_fma_f32 v141, -v139, v140, 1.0
	v_fmac_f32_e32 v135, v136, v135
	v_fmac_f32_e32 v140, v141, v140
	v_div_scale_f32 v137, vcc, 1.0, v226, 1.0
	v_mul_f32_e32 v138, v137, v135
	v_fma_f32 v136, -v134, v138, v137
	v_fmac_f32_e32 v138, v136, v135
	v_fma_f32 v134, -v134, v138, v137
	v_div_fmas_f32 v134, v134, v135, v138
	v_div_fixup_f32 v226, v134, v226, 1.0
	v_div_scale_f32 v165, vcc, 1.0, v227, 1.0
	v_mul_f32_e32 v166, v165, v140
	v_fma_f32 v141, -v139, v166, v165
	v_fmac_f32_e32 v166, v141, v140
	v_fma_f32 v139, -v139, v166, v165
	v_div_fmas_f32 v139, v139, v140, v166
	v_div_fixup_f32 v227, v139, v227, 1.0
	v_div_scale_f32 v134, s[2:3], v228, v228, 1.0
	v_div_scale_f32 v139, s[2:3], v229, v229, 1.0
	v_rcp_f32_e32 v135, v134
	v_rcp_f32_e32 v140, v139
	v_fma_f32 v136, -v134, v135, 1.0
	v_fma_f32 v141, -v139, v140, 1.0
	v_fmac_f32_e32 v135, v136, v135
	v_fmac_f32_e32 v140, v141, v140
	v_div_scale_f32 v137, vcc, 1.0, v228, 1.0
	v_mul_f32_e32 v138, v137, v135
	v_fma_f32 v136, -v134, v138, v137
	v_fmac_f32_e32 v138, v136, v135
	v_fma_f32 v134, -v134, v138, v137
	v_div_fmas_f32 v134, v134, v135, v138
	v_div_fixup_f32 v228, v134, v228, 1.0
	v_div_scale_f32 v165, vcc, 1.0, v229, 1.0
	v_mul_f32_e32 v166, v165, v140
	v_fma_f32 v141, -v139, v166, v165
	v_fmac_f32_e32 v166, v141, v140
	v_fma_f32 v139, -v139, v166, v165
	v_div_fmas_f32 v139, v139, v140, v166
	v_div_fixup_f32 v229, v139, v229, 1.0
	global_store_dwordx4 v[180:181], v[226:229], off offset:512
	v_add_f32_e32 v230, v118, v222
	v_add_f32_e32 v231, v119, v223
	v_add_f32_e32 v232, v120, v224
	v_add_f32_e32 v233, v121, v225
	v_mul_f32_e32 v230, 0xbfb8aa3b, v230
	v_mul_f32_e32 v231, 0xbfb8aa3b, v231
	v_mul_f32_e32 v232, 0xbfb8aa3b, v232
	v_mul_f32_e32 v233, 0xbfb8aa3b, v233
	v_exp_f32_e32 v230, v230
	v_exp_f32_e32 v231, v231
	v_exp_f32_e32 v232, v232
	v_exp_f32_e32 v233, v233
	v_add_f32_e32 v230, 1.0, v230
	v_add_f32_e32 v231, 1.0, v231
	v_add_f32_e32 v232, 1.0, v232
	v_add_f32_e32 v233, 1.0, v233
	v_div_scale_f32 v134, s[2:3], v230, v230, 1.0
	v_div_scale_f32 v139, s[2:3], v231, v231, 1.0
	v_rcp_f32_e32 v135, v134
	v_rcp_f32_e32 v140, v139
	v_fma_f32 v136, -v134, v135, 1.0
	v_fma_f32 v141, -v139, v140, 1.0
	v_fmac_f32_e32 v135, v136, v135
	v_fmac_f32_e32 v140, v141, v140
	v_div_scale_f32 v137, vcc, 1.0, v230, 1.0
	v_mul_f32_e32 v138, v137, v135
	v_fma_f32 v136, -v134, v138, v137
	v_fmac_f32_e32 v138, v136, v135
	v_fma_f32 v134, -v134, v138, v137
	v_div_fmas_f32 v134, v134, v135, v138
	v_div_fixup_f32 v230, v134, v230, 1.0
	v_div_scale_f32 v165, vcc, 1.0, v231, 1.0
	v_mul_f32_e32 v166, v165, v140
	v_fma_f32 v141, -v139, v166, v165
	v_fmac_f32_e32 v166, v141, v140
	v_fma_f32 v139, -v139, v166, v165
	v_div_fmas_f32 v139, v139, v140, v166
	v_div_fixup_f32 v231, v139, v231, 1.0
	v_div_scale_f32 v134, s[2:3], v232, v232, 1.0
	v_div_scale_f32 v139, s[2:3], v233, v233, 1.0
	v_rcp_f32_e32 v135, v134
	v_rcp_f32_e32 v140, v139
	v_fma_f32 v136, -v134, v135, 1.0
	v_fma_f32 v141, -v139, v140, 1.0
	v_fmac_f32_e32 v135, v136, v135
	v_fmac_f32_e32 v140, v141, v140
	v_div_scale_f32 v137, vcc, 1.0, v232, 1.0
	v_mul_f32_e32 v138, v137, v135
	v_fma_f32 v136, -v134, v138, v137
	v_fmac_f32_e32 v138, v136, v135
	v_fma_f32 v134, -v134, v138, v137
	v_div_fmas_f32 v134, v134, v135, v138
	v_div_fixup_f32 v232, v134, v232, 1.0
	v_div_scale_f32 v165, vcc, 1.0, v233, 1.0
	v_mul_f32_e32 v166, v165, v140
	v_fma_f32 v141, -v139, v166, v165
	v_fmac_f32_e32 v166, v141, v140
	v_fma_f32 v139, -v139, v166, v165
	v_div_fmas_f32 v139, v139, v140, v166
	v_div_fixup_f32 v233, v139, v233, 1.0
	global_store_dwordx4 v[180:181], v[230:233], off offset:576
	v_add_f32_e32 v226, v110, v210
	v_add_f32_e32 v227, v111, v211
	v_add_f32_e32 v228, v112, v212
	v_add_f32_e32 v229, v113, v213
	v_mul_f32_e32 v226, 0xbfb8aa3b, v226
	v_mul_f32_e32 v227, 0xbfb8aa3b, v227
	v_mul_f32_e32 v228, 0xbfb8aa3b, v228
	v_mul_f32_e32 v229, 0xbfb8aa3b, v229
	v_exp_f32_e32 v226, v226
	v_exp_f32_e32 v227, v227
	v_exp_f32_e32 v228, v228
	v_exp_f32_e32 v229, v229
	v_add_f32_e32 v226, 1.0, v226
	v_add_f32_e32 v227, 1.0, v227
	v_add_f32_e32 v228, 1.0, v228
	v_add_f32_e32 v229, 1.0, v229
	v_div_scale_f32 v134, s[2:3], v226, v226, 1.0
	v_div_scale_f32 v139, s[2:3], v227, v227, 1.0
	v_rcp_f32_e32 v135, v134
	v_rcp_f32_e32 v140, v139
	v_fma_f32 v136, -v134, v135, 1.0
	v_fma_f32 v141, -v139, v140, 1.0
	v_fmac_f32_e32 v135, v136, v135
	v_fmac_f32_e32 v140, v141, v140
	v_div_scale_f32 v137, vcc, 1.0, v226, 1.0
	v_mul_f32_e32 v138, v137, v135
	v_fma_f32 v136, -v134, v138, v137
	v_fmac_f32_e32 v138, v136, v135
	v_fma_f32 v134, -v134, v138, v137
	v_div_fmas_f32 v134, v134, v135, v138
	v_div_fixup_f32 v226, v134, v226, 1.0
	v_div_scale_f32 v165, vcc, 1.0, v227, 1.0
	v_mul_f32_e32 v166, v165, v140
	v_fma_f32 v141, -v139, v166, v165
	v_fmac_f32_e32 v166, v141, v140
	v_fma_f32 v139, -v139, v166, v165
	v_div_fmas_f32 v139, v139, v140, v166
	v_div_fixup_f32 v227, v139, v227, 1.0
	v_div_scale_f32 v134, s[2:3], v228, v228, 1.0
	v_div_scale_f32 v139, s[2:3], v229, v229, 1.0
	v_rcp_f32_e32 v135, v134
	v_rcp_f32_e32 v140, v139
	v_fma_f32 v136, -v134, v135, 1.0
	v_fma_f32 v141, -v139, v140, 1.0
	v_fmac_f32_e32 v135, v136, v135
	v_fmac_f32_e32 v140, v141, v140
	v_div_scale_f32 v137, vcc, 1.0, v228, 1.0
	v_mul_f32_e32 v138, v137, v135
	v_fma_f32 v136, -v134, v138, v137
	v_fmac_f32_e32 v138, v136, v135
	v_fma_f32 v134, -v134, v138, v137
	v_div_fmas_f32 v134, v134, v135, v138
	v_div_fixup_f32 v228, v134, v228, 1.0
	v_div_scale_f32 v165, vcc, 1.0, v229, 1.0
	v_mul_f32_e32 v166, v165, v140
	v_fma_f32 v141, -v139, v166, v165
	v_fmac_f32_e32 v166, v141, v140
	v_fma_f32 v139, -v139, v166, v165
	v_div_fmas_f32 v139, v139, v140, v166
	v_div_fixup_f32 v229, v139, v229, 1.0
	global_store_dwordx4 v[182:183], v[226:229], off
	v_add_f32_e32 v230, v106, v214
	v_add_f32_e32 v231, v107, v215
	v_add_f32_e32 v232, v108, v216
	v_add_f32_e32 v233, v109, v217
	v_mul_f32_e32 v230, 0xbfb8aa3b, v230
	v_mul_f32_e32 v231, 0xbfb8aa3b, v231
	v_mul_f32_e32 v232, 0xbfb8aa3b, v232
	v_mul_f32_e32 v233, 0xbfb8aa3b, v233
	v_exp_f32_e32 v230, v230
	v_exp_f32_e32 v231, v231
	v_exp_f32_e32 v232, v232
	v_exp_f32_e32 v233, v233
	v_add_f32_e32 v230, 1.0, v230
	v_add_f32_e32 v231, 1.0, v231
	v_add_f32_e32 v232, 1.0, v232
	v_add_f32_e32 v233, 1.0, v233
	v_div_scale_f32 v134, s[2:3], v230, v230, 1.0
	v_div_scale_f32 v139, s[2:3], v231, v231, 1.0
	v_rcp_f32_e32 v135, v134
	v_rcp_f32_e32 v140, v139
	v_fma_f32 v136, -v134, v135, 1.0
	v_fma_f32 v141, -v139, v140, 1.0
	v_fmac_f32_e32 v135, v136, v135
	v_fmac_f32_e32 v140, v141, v140
	v_div_scale_f32 v137, vcc, 1.0, v230, 1.0
	v_mul_f32_e32 v138, v137, v135
	v_fma_f32 v136, -v134, v138, v137
	v_fmac_f32_e32 v138, v136, v135
	v_fma_f32 v134, -v134, v138, v137
	v_div_fmas_f32 v134, v134, v135, v138
	v_div_fixup_f32 v230, v134, v230, 1.0
	v_div_scale_f32 v165, vcc, 1.0, v231, 1.0
	v_mul_f32_e32 v166, v165, v140
	v_fma_f32 v141, -v139, v166, v165
	v_fmac_f32_e32 v166, v141, v140
	v_fma_f32 v139, -v139, v166, v165
	v_div_fmas_f32 v139, v139, v140, v166
	v_div_fixup_f32 v231, v139, v231, 1.0
	v_div_scale_f32 v134, s[2:3], v232, v232, 1.0
	v_div_scale_f32 v139, s[2:3], v233, v233, 1.0
	v_rcp_f32_e32 v135, v134
	v_rcp_f32_e32 v140, v139
	v_fma_f32 v136, -v134, v135, 1.0
	v_fma_f32 v141, -v139, v140, 1.0
	v_fmac_f32_e32 v135, v136, v135
	v_fmac_f32_e32 v140, v141, v140
	v_div_scale_f32 v137, vcc, 1.0, v232, 1.0
	v_mul_f32_e32 v138, v137, v135
	v_fma_f32 v136, -v134, v138, v137
	v_fmac_f32_e32 v138, v136, v135
	v_fma_f32 v134, -v134, v138, v137
	v_div_fmas_f32 v134, v134, v135, v138
	v_div_fixup_f32 v232, v134, v232, 1.0
	v_div_scale_f32 v165, vcc, 1.0, v233, 1.0
	v_mul_f32_e32 v166, v165, v140
	v_fma_f32 v141, -v139, v166, v165
	v_fmac_f32_e32 v166, v141, v140
	v_fma_f32 v139, -v139, v166, v165
	v_div_fmas_f32 v139, v139, v140, v166
	v_div_fixup_f32 v233, v139, v233, 1.0
	global_store_dwordx4 v[182:183], v[230:233], off offset:64
	v_add_f32_e32 v226, v102, v218
	v_add_f32_e32 v227, v103, v219
	v_add_f32_e32 v228, v104, v220
	v_add_f32_e32 v229, v105, v221
	v_mul_f32_e32 v226, 0xbfb8aa3b, v226
	v_mul_f32_e32 v227, 0xbfb8aa3b, v227
	v_mul_f32_e32 v228, 0xbfb8aa3b, v228
	v_mul_f32_e32 v229, 0xbfb8aa3b, v229
	v_exp_f32_e32 v226, v226
	v_exp_f32_e32 v227, v227
	v_exp_f32_e32 v228, v228
	v_exp_f32_e32 v229, v229
	v_add_f32_e32 v226, 1.0, v226
	v_add_f32_e32 v227, 1.0, v227
	v_add_f32_e32 v228, 1.0, v228
	v_add_f32_e32 v229, 1.0, v229
	v_div_scale_f32 v134, s[2:3], v226, v226, 1.0
	v_div_scale_f32 v139, s[2:3], v227, v227, 1.0
	v_rcp_f32_e32 v135, v134
	v_rcp_f32_e32 v140, v139
	v_fma_f32 v136, -v134, v135, 1.0
	v_fma_f32 v141, -v139, v140, 1.0
	v_fmac_f32_e32 v135, v136, v135
	v_fmac_f32_e32 v140, v141, v140
	v_div_scale_f32 v137, vcc, 1.0, v226, 1.0
	v_mul_f32_e32 v138, v137, v135
	v_fma_f32 v136, -v134, v138, v137
	v_fmac_f32_e32 v138, v136, v135
	v_fma_f32 v134, -v134, v138, v137
	v_div_fmas_f32 v134, v134, v135, v138
	v_div_fixup_f32 v226, v134, v226, 1.0
	v_div_scale_f32 v165, vcc, 1.0, v227, 1.0
	v_mul_f32_e32 v166, v165, v140
	v_fma_f32 v141, -v139, v166, v165
	v_fmac_f32_e32 v166, v141, v140
	v_fma_f32 v139, -v139, v166, v165
	v_div_fmas_f32 v139, v139, v140, v166
	v_div_fixup_f32 v227, v139, v227, 1.0
	v_div_scale_f32 v134, s[2:3], v228, v228, 1.0
	v_div_scale_f32 v139, s[2:3], v229, v229, 1.0
	v_rcp_f32_e32 v135, v134
	v_rcp_f32_e32 v140, v139
	v_fma_f32 v136, -v134, v135, 1.0
	v_fma_f32 v141, -v139, v140, 1.0
	v_fmac_f32_e32 v135, v136, v135
	v_fmac_f32_e32 v140, v141, v140
	v_div_scale_f32 v137, vcc, 1.0, v228, 1.0
	v_mul_f32_e32 v138, v137, v135
	v_fma_f32 v136, -v134, v138, v137
	v_fmac_f32_e32 v138, v136, v135
	v_fma_f32 v134, -v134, v138, v137
	v_div_fmas_f32 v134, v134, v135, v138
	v_div_fixup_f32 v228, v134, v228, 1.0
	v_div_scale_f32 v165, vcc, 1.0, v229, 1.0
	v_mul_f32_e32 v166, v165, v140
	v_fma_f32 v141, -v139, v166, v165
	v_fmac_f32_e32 v166, v141, v140
	v_fma_f32 v139, -v139, v166, v165
	v_div_fmas_f32 v139, v139, v140, v166
	v_div_fixup_f32 v229, v139, v229, 1.0
	global_store_dwordx4 v[182:183], v[226:229], off offset:512
	v_add_f32_e32 v230, v98, v222
	v_add_f32_e32 v231, v99, v223
	v_add_f32_e32 v232, v100, v224
	v_add_f32_e32 v233, v101, v225
	v_mul_f32_e32 v230, 0xbfb8aa3b, v230
	v_mul_f32_e32 v231, 0xbfb8aa3b, v231
	v_mul_f32_e32 v232, 0xbfb8aa3b, v232
	v_mul_f32_e32 v233, 0xbfb8aa3b, v233
	v_exp_f32_e32 v230, v230
	v_exp_f32_e32 v231, v231
	v_exp_f32_e32 v232, v232
	v_exp_f32_e32 v233, v233
	v_add_f32_e32 v230, 1.0, v230
	v_add_f32_e32 v231, 1.0, v231
	v_add_f32_e32 v232, 1.0, v232
	v_add_f32_e32 v233, 1.0, v233
	v_div_scale_f32 v134, s[2:3], v230, v230, 1.0
	v_div_scale_f32 v139, s[2:3], v231, v231, 1.0
	v_rcp_f32_e32 v135, v134
	v_rcp_f32_e32 v140, v139
	v_fma_f32 v136, -v134, v135, 1.0
	v_fma_f32 v141, -v139, v140, 1.0
	v_fmac_f32_e32 v135, v136, v135
	v_fmac_f32_e32 v140, v141, v140
	v_div_scale_f32 v137, vcc, 1.0, v230, 1.0
	v_mul_f32_e32 v138, v137, v135
	v_fma_f32 v136, -v134, v138, v137
	v_fmac_f32_e32 v138, v136, v135
	v_fma_f32 v134, -v134, v138, v137
	v_div_fmas_f32 v134, v134, v135, v138
	v_div_fixup_f32 v230, v134, v230, 1.0
	v_div_scale_f32 v165, vcc, 1.0, v231, 1.0
	v_mul_f32_e32 v166, v165, v140
	v_fma_f32 v141, -v139, v166, v165
	v_fmac_f32_e32 v166, v141, v140
	v_fma_f32 v139, -v139, v166, v165
	v_div_fmas_f32 v139, v139, v140, v166
	v_div_fixup_f32 v231, v139, v231, 1.0
	v_div_scale_f32 v134, s[2:3], v232, v232, 1.0
	v_div_scale_f32 v139, s[2:3], v233, v233, 1.0
	v_rcp_f32_e32 v135, v134
	v_rcp_f32_e32 v140, v139
	v_fma_f32 v136, -v134, v135, 1.0
	v_fma_f32 v141, -v139, v140, 1.0
	v_fmac_f32_e32 v135, v136, v135
	v_fmac_f32_e32 v140, v141, v140
	v_div_scale_f32 v137, vcc, 1.0, v232, 1.0
	v_mul_f32_e32 v138, v137, v135
	v_fma_f32 v136, -v134, v138, v137
	v_fmac_f32_e32 v138, v136, v135
	v_fma_f32 v134, -v134, v138, v137
	v_div_fmas_f32 v134, v134, v135, v138
	v_div_fixup_f32 v232, v134, v232, 1.0
	v_div_scale_f32 v165, vcc, 1.0, v233, 1.0
	v_mul_f32_e32 v166, v165, v140
	v_fma_f32 v141, -v139, v166, v165
	v_fmac_f32_e32 v166, v141, v140
	v_fma_f32 v139, -v139, v166, v165
	v_div_fmas_f32 v139, v139, v140, v166
	v_div_fixup_f32 v233, v139, v233, 1.0
	global_store_dwordx4 v[182:183], v[230:233], off offset:576
	v_add_f32_e32 v226, v94, v210
	v_add_f32_e32 v227, v95, v211
	v_add_f32_e32 v228, v96, v212
	v_add_f32_e32 v229, v97, v213
	v_mul_f32_e32 v226, 0xbfb8aa3b, v226
	v_mul_f32_e32 v227, 0xbfb8aa3b, v227
	v_mul_f32_e32 v228, 0xbfb8aa3b, v228
	v_mul_f32_e32 v229, 0xbfb8aa3b, v229
	v_exp_f32_e32 v226, v226
	v_exp_f32_e32 v227, v227
	v_exp_f32_e32 v228, v228
	v_exp_f32_e32 v229, v229
	v_add_f32_e32 v226, 1.0, v226
	v_add_f32_e32 v227, 1.0, v227
	v_add_f32_e32 v228, 1.0, v228
	v_add_f32_e32 v229, 1.0, v229
	v_div_scale_f32 v134, s[2:3], v226, v226, 1.0
	v_div_scale_f32 v139, s[2:3], v227, v227, 1.0
	v_rcp_f32_e32 v135, v134
	v_rcp_f32_e32 v140, v139
	v_fma_f32 v136, -v134, v135, 1.0
	v_fma_f32 v141, -v139, v140, 1.0
	v_fmac_f32_e32 v135, v136, v135
	v_fmac_f32_e32 v140, v141, v140
	v_div_scale_f32 v137, vcc, 1.0, v226, 1.0
	v_mul_f32_e32 v138, v137, v135
	v_fma_f32 v136, -v134, v138, v137
	v_fmac_f32_e32 v138, v136, v135
	v_fma_f32 v134, -v134, v138, v137
	v_div_fmas_f32 v134, v134, v135, v138
	v_div_fixup_f32 v226, v134, v226, 1.0
	v_div_scale_f32 v165, vcc, 1.0, v227, 1.0
	v_mul_f32_e32 v166, v165, v140
	v_fma_f32 v141, -v139, v166, v165
	v_fmac_f32_e32 v166, v141, v140
	v_fma_f32 v139, -v139, v166, v165
	v_div_fmas_f32 v139, v139, v140, v166
	v_div_fixup_f32 v227, v139, v227, 1.0
	v_div_scale_f32 v134, s[2:3], v228, v228, 1.0
	v_div_scale_f32 v139, s[2:3], v229, v229, 1.0
	v_rcp_f32_e32 v135, v134
	v_rcp_f32_e32 v140, v139
	v_fma_f32 v136, -v134, v135, 1.0
	v_fma_f32 v141, -v139, v140, 1.0
	v_fmac_f32_e32 v135, v136, v135
	v_fmac_f32_e32 v140, v141, v140
	v_div_scale_f32 v137, vcc, 1.0, v228, 1.0
	v_mul_f32_e32 v138, v137, v135
	v_fma_f32 v136, -v134, v138, v137
	v_fmac_f32_e32 v138, v136, v135
	v_fma_f32 v134, -v134, v138, v137
	v_div_fmas_f32 v134, v134, v135, v138
	v_div_fixup_f32 v228, v134, v228, 1.0
	v_div_scale_f32 v165, vcc, 1.0, v229, 1.0
	v_mul_f32_e32 v166, v165, v140
	v_fma_f32 v141, -v139, v166, v165
	v_fmac_f32_e32 v166, v141, v140
	v_fma_f32 v139, -v139, v166, v165
	v_div_fmas_f32 v139, v139, v140, v166
	v_div_fixup_f32 v229, v139, v229, 1.0
	global_store_dwordx4 v[184:185], v[226:229], off
	v_add_f32_e32 v230, v90, v214
	v_add_f32_e32 v231, v91, v215
	v_add_f32_e32 v232, v92, v216
	v_add_f32_e32 v233, v93, v217
	v_mul_f32_e32 v230, 0xbfb8aa3b, v230
	v_mul_f32_e32 v231, 0xbfb8aa3b, v231
	v_mul_f32_e32 v232, 0xbfb8aa3b, v232
	v_mul_f32_e32 v233, 0xbfb8aa3b, v233
	v_exp_f32_e32 v230, v230
	v_exp_f32_e32 v231, v231
	v_exp_f32_e32 v232, v232
	v_exp_f32_e32 v233, v233
	v_add_f32_e32 v230, 1.0, v230
	v_add_f32_e32 v231, 1.0, v231
	v_add_f32_e32 v232, 1.0, v232
	v_add_f32_e32 v233, 1.0, v233
	v_div_scale_f32 v134, s[2:3], v230, v230, 1.0
	v_div_scale_f32 v139, s[2:3], v231, v231, 1.0
	v_rcp_f32_e32 v135, v134
	v_rcp_f32_e32 v140, v139
	v_fma_f32 v136, -v134, v135, 1.0
	v_fma_f32 v141, -v139, v140, 1.0
	v_fmac_f32_e32 v135, v136, v135
	v_fmac_f32_e32 v140, v141, v140
	v_div_scale_f32 v137, vcc, 1.0, v230, 1.0
	v_mul_f32_e32 v138, v137, v135
	v_fma_f32 v136, -v134, v138, v137
	v_fmac_f32_e32 v138, v136, v135
	v_fma_f32 v134, -v134, v138, v137
	v_div_fmas_f32 v134, v134, v135, v138
	v_div_fixup_f32 v230, v134, v230, 1.0
	v_div_scale_f32 v165, vcc, 1.0, v231, 1.0
	v_mul_f32_e32 v166, v165, v140
	v_fma_f32 v141, -v139, v166, v165
	v_fmac_f32_e32 v166, v141, v140
	v_fma_f32 v139, -v139, v166, v165
	v_div_fmas_f32 v139, v139, v140, v166
	v_div_fixup_f32 v231, v139, v231, 1.0
	v_div_scale_f32 v134, s[2:3], v232, v232, 1.0
	v_div_scale_f32 v139, s[2:3], v233, v233, 1.0
	v_rcp_f32_e32 v135, v134
	v_rcp_f32_e32 v140, v139
	v_fma_f32 v136, -v134, v135, 1.0
	v_fma_f32 v141, -v139, v140, 1.0
	v_fmac_f32_e32 v135, v136, v135
	v_fmac_f32_e32 v140, v141, v140
	v_div_scale_f32 v137, vcc, 1.0, v232, 1.0
	v_mul_f32_e32 v138, v137, v135
	v_fma_f32 v136, -v134, v138, v137
	v_fmac_f32_e32 v138, v136, v135
	v_fma_f32 v134, -v134, v138, v137
	v_div_fmas_f32 v134, v134, v135, v138
	v_div_fixup_f32 v232, v134, v232, 1.0
	v_div_scale_f32 v165, vcc, 1.0, v233, 1.0
	v_mul_f32_e32 v166, v165, v140
	v_fma_f32 v141, -v139, v166, v165
	v_fmac_f32_e32 v166, v141, v140
	v_fma_f32 v139, -v139, v166, v165
	v_div_fmas_f32 v139, v139, v140, v166
	v_div_fixup_f32 v233, v139, v233, 1.0
	global_store_dwordx4 v[184:185], v[230:233], off offset:64
	v_add_f32_e32 v226, v86, v218
	v_add_f32_e32 v227, v87, v219
	v_add_f32_e32 v228, v88, v220
	v_add_f32_e32 v229, v89, v221
	v_mul_f32_e32 v226, 0xbfb8aa3b, v226
	v_mul_f32_e32 v227, 0xbfb8aa3b, v227
	v_mul_f32_e32 v228, 0xbfb8aa3b, v228
	v_mul_f32_e32 v229, 0xbfb8aa3b, v229
	v_exp_f32_e32 v226, v226
	v_exp_f32_e32 v227, v227
	v_exp_f32_e32 v228, v228
	v_exp_f32_e32 v229, v229
	v_add_f32_e32 v226, 1.0, v226
	v_add_f32_e32 v227, 1.0, v227
	v_add_f32_e32 v228, 1.0, v228
	v_add_f32_e32 v229, 1.0, v229
	v_div_scale_f32 v134, s[2:3], v226, v226, 1.0
	v_div_scale_f32 v139, s[2:3], v227, v227, 1.0
	v_rcp_f32_e32 v135, v134
	v_rcp_f32_e32 v140, v139
	v_fma_f32 v136, -v134, v135, 1.0
	v_fma_f32 v141, -v139, v140, 1.0
	v_fmac_f32_e32 v135, v136, v135
	v_fmac_f32_e32 v140, v141, v140
	v_div_scale_f32 v137, vcc, 1.0, v226, 1.0
	v_mul_f32_e32 v138, v137, v135
	v_fma_f32 v136, -v134, v138, v137
	v_fmac_f32_e32 v138, v136, v135
	v_fma_f32 v134, -v134, v138, v137
	v_div_fmas_f32 v134, v134, v135, v138
	v_div_fixup_f32 v226, v134, v226, 1.0
	v_div_scale_f32 v165, vcc, 1.0, v227, 1.0
	v_mul_f32_e32 v166, v165, v140
	v_fma_f32 v141, -v139, v166, v165
	v_fmac_f32_e32 v166, v141, v140
	v_fma_f32 v139, -v139, v166, v165
	v_div_fmas_f32 v139, v139, v140, v166
	v_div_fixup_f32 v227, v139, v227, 1.0
	v_div_scale_f32 v134, s[2:3], v228, v228, 1.0
	v_div_scale_f32 v139, s[2:3], v229, v229, 1.0
	v_rcp_f32_e32 v135, v134
	v_rcp_f32_e32 v140, v139
	v_fma_f32 v136, -v134, v135, 1.0
	v_fma_f32 v141, -v139, v140, 1.0
	v_fmac_f32_e32 v135, v136, v135
	v_fmac_f32_e32 v140, v141, v140
	v_div_scale_f32 v137, vcc, 1.0, v228, 1.0
	v_mul_f32_e32 v138, v137, v135
	v_fma_f32 v136, -v134, v138, v137
	v_fmac_f32_e32 v138, v136, v135
	v_fma_f32 v134, -v134, v138, v137
	v_div_fmas_f32 v134, v134, v135, v138
	v_div_fixup_f32 v228, v134, v228, 1.0
	v_div_scale_f32 v165, vcc, 1.0, v229, 1.0
	v_mul_f32_e32 v166, v165, v140
	v_fma_f32 v141, -v139, v166, v165
	v_fmac_f32_e32 v166, v141, v140
	v_fma_f32 v139, -v139, v166, v165
	v_div_fmas_f32 v139, v139, v140, v166
	v_div_fixup_f32 v229, v139, v229, 1.0
	global_store_dwordx4 v[184:185], v[226:229], off offset:512
	v_add_f32_e32 v230, v82, v222
	v_add_f32_e32 v231, v83, v223
	v_add_f32_e32 v232, v84, v224
	v_add_f32_e32 v233, v85, v225
	v_mul_f32_e32 v230, 0xbfb8aa3b, v230
	v_mul_f32_e32 v231, 0xbfb8aa3b, v231
	v_mul_f32_e32 v232, 0xbfb8aa3b, v232
	v_mul_f32_e32 v233, 0xbfb8aa3b, v233
	v_exp_f32_e32 v230, v230
	v_exp_f32_e32 v231, v231
	v_exp_f32_e32 v232, v232
	v_exp_f32_e32 v233, v233
	v_add_f32_e32 v230, 1.0, v230
	v_add_f32_e32 v231, 1.0, v231
	v_add_f32_e32 v232, 1.0, v232
	v_add_f32_e32 v233, 1.0, v233
	v_div_scale_f32 v134, s[2:3], v230, v230, 1.0
	v_div_scale_f32 v139, s[2:3], v231, v231, 1.0
	v_rcp_f32_e32 v135, v134
	v_rcp_f32_e32 v140, v139
	v_fma_f32 v136, -v134, v135, 1.0
	v_fma_f32 v141, -v139, v140, 1.0
	v_fmac_f32_e32 v135, v136, v135
	v_fmac_f32_e32 v140, v141, v140
	v_div_scale_f32 v137, vcc, 1.0, v230, 1.0
	v_mul_f32_e32 v138, v137, v135
	v_fma_f32 v136, -v134, v138, v137
	v_fmac_f32_e32 v138, v136, v135
	v_fma_f32 v134, -v134, v138, v137
	v_div_fmas_f32 v134, v134, v135, v138
	v_div_fixup_f32 v230, v134, v230, 1.0
	v_div_scale_f32 v165, vcc, 1.0, v231, 1.0
	v_mul_f32_e32 v166, v165, v140
	v_fma_f32 v141, -v139, v166, v165
	v_fmac_f32_e32 v166, v141, v140
	v_fma_f32 v139, -v139, v166, v165
	v_div_fmas_f32 v139, v139, v140, v166
	v_div_fixup_f32 v231, v139, v231, 1.0
	v_div_scale_f32 v134, s[2:3], v232, v232, 1.0
	v_div_scale_f32 v139, s[2:3], v233, v233, 1.0
	v_rcp_f32_e32 v135, v134
	v_rcp_f32_e32 v140, v139
	v_fma_f32 v136, -v134, v135, 1.0
	v_fma_f32 v141, -v139, v140, 1.0
	v_fmac_f32_e32 v135, v136, v135
	v_fmac_f32_e32 v140, v141, v140
	v_div_scale_f32 v137, vcc, 1.0, v232, 1.0
	v_mul_f32_e32 v138, v137, v135
	v_fma_f32 v136, -v134, v138, v137
	v_fmac_f32_e32 v138, v136, v135
	v_fma_f32 v134, -v134, v138, v137
	v_div_fmas_f32 v134, v134, v135, v138
	v_div_fixup_f32 v232, v134, v232, 1.0
	v_div_scale_f32 v165, vcc, 1.0, v233, 1.0
	v_mul_f32_e32 v166, v165, v140
	v_fma_f32 v141, -v139, v166, v165
	v_fmac_f32_e32 v166, v141, v140
	v_fma_f32 v139, -v139, v166, v165
	v_div_fmas_f32 v139, v139, v140, v166
	v_div_fixup_f32 v233, v139, v233, 1.0
	global_store_dwordx4 v[184:185], v[230:233], off offset:576
	v_add_f32_e32 v226, v78, v210
	v_add_f32_e32 v227, v79, v211
	v_add_f32_e32 v228, v80, v212
	v_add_f32_e32 v229, v81, v213
	v_mul_f32_e32 v226, 0xbfb8aa3b, v226
	v_mul_f32_e32 v227, 0xbfb8aa3b, v227
	v_mul_f32_e32 v228, 0xbfb8aa3b, v228
	v_mul_f32_e32 v229, 0xbfb8aa3b, v229
	v_exp_f32_e32 v226, v226
	v_exp_f32_e32 v227, v227
	v_exp_f32_e32 v228, v228
	v_exp_f32_e32 v229, v229
	v_add_f32_e32 v226, 1.0, v226
	v_add_f32_e32 v227, 1.0, v227
	v_add_f32_e32 v228, 1.0, v228
	v_add_f32_e32 v229, 1.0, v229
	v_div_scale_f32 v134, s[2:3], v226, v226, 1.0
	v_div_scale_f32 v139, s[2:3], v227, v227, 1.0
	v_rcp_f32_e32 v135, v134
	v_rcp_f32_e32 v140, v139
	v_fma_f32 v136, -v134, v135, 1.0
	v_fma_f32 v141, -v139, v140, 1.0
	v_fmac_f32_e32 v135, v136, v135
	v_fmac_f32_e32 v140, v141, v140
	v_div_scale_f32 v137, vcc, 1.0, v226, 1.0
	v_mul_f32_e32 v138, v137, v135
	v_fma_f32 v136, -v134, v138, v137
	v_fmac_f32_e32 v138, v136, v135
	v_fma_f32 v134, -v134, v138, v137
	v_div_fmas_f32 v134, v134, v135, v138
	v_div_fixup_f32 v226, v134, v226, 1.0
	v_div_scale_f32 v165, vcc, 1.0, v227, 1.0
	v_mul_f32_e32 v166, v165, v140
	v_fma_f32 v141, -v139, v166, v165
	v_fmac_f32_e32 v166, v141, v140
	v_fma_f32 v139, -v139, v166, v165
	v_div_fmas_f32 v139, v139, v140, v166
	v_div_fixup_f32 v227, v139, v227, 1.0
	v_div_scale_f32 v134, s[2:3], v228, v228, 1.0
	v_div_scale_f32 v139, s[2:3], v229, v229, 1.0
	v_rcp_f32_e32 v135, v134
	v_rcp_f32_e32 v140, v139
	v_fma_f32 v136, -v134, v135, 1.0
	v_fma_f32 v141, -v139, v140, 1.0
	v_fmac_f32_e32 v135, v136, v135
	v_fmac_f32_e32 v140, v141, v140
	v_div_scale_f32 v137, vcc, 1.0, v228, 1.0
	v_mul_f32_e32 v138, v137, v135
	v_fma_f32 v136, -v134, v138, v137
	v_fmac_f32_e32 v138, v136, v135
	v_fma_f32 v134, -v134, v138, v137
	v_div_fmas_f32 v134, v134, v135, v138
	v_div_fixup_f32 v228, v134, v228, 1.0
	v_div_scale_f32 v165, vcc, 1.0, v229, 1.0
	v_mul_f32_e32 v166, v165, v140
	v_fma_f32 v141, -v139, v166, v165
	v_fmac_f32_e32 v166, v141, v140
	v_fma_f32 v139, -v139, v166, v165
	v_div_fmas_f32 v139, v139, v140, v166
	v_div_fixup_f32 v229, v139, v229, 1.0
	global_store_dwordx4 v[186:187], v[226:229], off
	v_add_f32_e32 v230, v74, v214
	v_add_f32_e32 v231, v75, v215
	v_add_f32_e32 v232, v76, v216
	v_add_f32_e32 v233, v77, v217
	v_mul_f32_e32 v230, 0xbfb8aa3b, v230
	v_mul_f32_e32 v231, 0xbfb8aa3b, v231
	v_mul_f32_e32 v232, 0xbfb8aa3b, v232
	v_mul_f32_e32 v233, 0xbfb8aa3b, v233
	v_exp_f32_e32 v230, v230
	v_exp_f32_e32 v231, v231
	v_exp_f32_e32 v232, v232
	v_exp_f32_e32 v233, v233
	v_add_f32_e32 v230, 1.0, v230
	v_add_f32_e32 v231, 1.0, v231
	v_add_f32_e32 v232, 1.0, v232
	v_add_f32_e32 v233, 1.0, v233
	v_div_scale_f32 v134, s[2:3], v230, v230, 1.0
	v_div_scale_f32 v139, s[2:3], v231, v231, 1.0
	v_rcp_f32_e32 v135, v134
	v_rcp_f32_e32 v140, v139
	v_fma_f32 v136, -v134, v135, 1.0
	v_fma_f32 v141, -v139, v140, 1.0
	v_fmac_f32_e32 v135, v136, v135
	v_fmac_f32_e32 v140, v141, v140
	v_div_scale_f32 v137, vcc, 1.0, v230, 1.0
	v_mul_f32_e32 v138, v137, v135
	v_fma_f32 v136, -v134, v138, v137
	v_fmac_f32_e32 v138, v136, v135
	v_fma_f32 v134, -v134, v138, v137
	v_div_fmas_f32 v134, v134, v135, v138
	v_div_fixup_f32 v230, v134, v230, 1.0
	v_div_scale_f32 v165, vcc, 1.0, v231, 1.0
	v_mul_f32_e32 v166, v165, v140
	v_fma_f32 v141, -v139, v166, v165
	v_fmac_f32_e32 v166, v141, v140
	v_fma_f32 v139, -v139, v166, v165
	v_div_fmas_f32 v139, v139, v140, v166
	v_div_fixup_f32 v231, v139, v231, 1.0
	v_div_scale_f32 v134, s[2:3], v232, v232, 1.0
	v_div_scale_f32 v139, s[2:3], v233, v233, 1.0
	v_rcp_f32_e32 v135, v134
	v_rcp_f32_e32 v140, v139
	v_fma_f32 v136, -v134, v135, 1.0
	v_fma_f32 v141, -v139, v140, 1.0
	v_fmac_f32_e32 v135, v136, v135
	v_fmac_f32_e32 v140, v141, v140
	v_div_scale_f32 v137, vcc, 1.0, v232, 1.0
	v_mul_f32_e32 v138, v137, v135
	v_fma_f32 v136, -v134, v138, v137
	v_fmac_f32_e32 v138, v136, v135
	v_fma_f32 v134, -v134, v138, v137
	v_div_fmas_f32 v134, v134, v135, v138
	v_div_fixup_f32 v232, v134, v232, 1.0
	v_div_scale_f32 v165, vcc, 1.0, v233, 1.0
	v_mul_f32_e32 v166, v165, v140
	v_fma_f32 v141, -v139, v166, v165
	v_fmac_f32_e32 v166, v141, v140
	v_fma_f32 v139, -v139, v166, v165
	v_div_fmas_f32 v139, v139, v140, v166
	v_div_fixup_f32 v233, v139, v233, 1.0
	global_store_dwordx4 v[186:187], v[230:233], off offset:64
	v_add_f32_e32 v226, v70, v218
	v_add_f32_e32 v227, v71, v219
	v_add_f32_e32 v228, v72, v220
	v_add_f32_e32 v229, v73, v221
	v_mul_f32_e32 v226, 0xbfb8aa3b, v226
	v_mul_f32_e32 v227, 0xbfb8aa3b, v227
	v_mul_f32_e32 v228, 0xbfb8aa3b, v228
	v_mul_f32_e32 v229, 0xbfb8aa3b, v229
	v_exp_f32_e32 v226, v226
	v_exp_f32_e32 v227, v227
	v_exp_f32_e32 v228, v228
	v_exp_f32_e32 v229, v229
	v_add_f32_e32 v226, 1.0, v226
	v_add_f32_e32 v227, 1.0, v227
	v_add_f32_e32 v228, 1.0, v228
	v_add_f32_e32 v229, 1.0, v229
	v_div_scale_f32 v134, s[2:3], v226, v226, 1.0
	v_div_scale_f32 v139, s[2:3], v227, v227, 1.0
	v_rcp_f32_e32 v135, v134
	v_rcp_f32_e32 v140, v139
	v_fma_f32 v136, -v134, v135, 1.0
	v_fma_f32 v141, -v139, v140, 1.0
	v_fmac_f32_e32 v135, v136, v135
	v_fmac_f32_e32 v140, v141, v140
	v_div_scale_f32 v137, vcc, 1.0, v226, 1.0
	v_mul_f32_e32 v138, v137, v135
	v_fma_f32 v136, -v134, v138, v137
	v_fmac_f32_e32 v138, v136, v135
	v_fma_f32 v134, -v134, v138, v137
	v_div_fmas_f32 v134, v134, v135, v138
	v_div_fixup_f32 v226, v134, v226, 1.0
	v_div_scale_f32 v165, vcc, 1.0, v227, 1.0
	v_mul_f32_e32 v166, v165, v140
	v_fma_f32 v141, -v139, v166, v165
	v_fmac_f32_e32 v166, v141, v140
	v_fma_f32 v139, -v139, v166, v165
	v_div_fmas_f32 v139, v139, v140, v166
	v_div_fixup_f32 v227, v139, v227, 1.0
	v_div_scale_f32 v134, s[2:3], v228, v228, 1.0
	v_div_scale_f32 v139, s[2:3], v229, v229, 1.0
	v_rcp_f32_e32 v135, v134
	v_rcp_f32_e32 v140, v139
	v_fma_f32 v136, -v134, v135, 1.0
	v_fma_f32 v141, -v139, v140, 1.0
	v_fmac_f32_e32 v135, v136, v135
	v_fmac_f32_e32 v140, v141, v140
	v_div_scale_f32 v137, vcc, 1.0, v228, 1.0
	v_mul_f32_e32 v138, v137, v135
	v_fma_f32 v136, -v134, v138, v137
	v_fmac_f32_e32 v138, v136, v135
	v_fma_f32 v134, -v134, v138, v137
	v_div_fmas_f32 v134, v134, v135, v138
	v_div_fixup_f32 v228, v134, v228, 1.0
	v_div_scale_f32 v165, vcc, 1.0, v229, 1.0
	v_mul_f32_e32 v166, v165, v140
	v_fma_f32 v141, -v139, v166, v165
	v_fmac_f32_e32 v166, v141, v140
	v_fma_f32 v139, -v139, v166, v165
	v_div_fmas_f32 v139, v139, v140, v166
	v_div_fixup_f32 v229, v139, v229, 1.0
	global_store_dwordx4 v[186:187], v[226:229], off offset:512
	v_add_f32_e32 v230, v66, v222
	v_add_f32_e32 v231, v67, v223
	v_add_f32_e32 v232, v68, v224
	v_add_f32_e32 v233, v69, v225
	v_mul_f32_e32 v230, 0xbfb8aa3b, v230
	v_mul_f32_e32 v231, 0xbfb8aa3b, v231
	v_mul_f32_e32 v232, 0xbfb8aa3b, v232
	v_mul_f32_e32 v233, 0xbfb8aa3b, v233
	v_exp_f32_e32 v230, v230
	v_exp_f32_e32 v231, v231
	v_exp_f32_e32 v232, v232
	v_exp_f32_e32 v233, v233
	v_add_f32_e32 v230, 1.0, v230
	v_add_f32_e32 v231, 1.0, v231
	v_add_f32_e32 v232, 1.0, v232
	v_add_f32_e32 v233, 1.0, v233
	v_div_scale_f32 v134, s[2:3], v230, v230, 1.0
	v_div_scale_f32 v139, s[2:3], v231, v231, 1.0
	v_rcp_f32_e32 v135, v134
	v_rcp_f32_e32 v140, v139
	v_fma_f32 v136, -v134, v135, 1.0
	v_fma_f32 v141, -v139, v140, 1.0
	v_fmac_f32_e32 v135, v136, v135
	v_fmac_f32_e32 v140, v141, v140
	v_div_scale_f32 v137, vcc, 1.0, v230, 1.0
	v_mul_f32_e32 v138, v137, v135
	v_fma_f32 v136, -v134, v138, v137
	v_fmac_f32_e32 v138, v136, v135
	v_fma_f32 v134, -v134, v138, v137
	v_div_fmas_f32 v134, v134, v135, v138
	v_div_fixup_f32 v230, v134, v230, 1.0
	v_div_scale_f32 v165, vcc, 1.0, v231, 1.0
	v_mul_f32_e32 v166, v165, v140
	v_fma_f32 v141, -v139, v166, v165
	v_fmac_f32_e32 v166, v141, v140
	v_fma_f32 v139, -v139, v166, v165
	v_div_fmas_f32 v139, v139, v140, v166
	v_div_fixup_f32 v231, v139, v231, 1.0
	v_div_scale_f32 v134, s[2:3], v232, v232, 1.0
	v_div_scale_f32 v139, s[2:3], v233, v233, 1.0
	v_rcp_f32_e32 v135, v134
	v_rcp_f32_e32 v140, v139
	v_fma_f32 v136, -v134, v135, 1.0
	v_fma_f32 v141, -v139, v140, 1.0
	v_fmac_f32_e32 v135, v136, v135
	v_fmac_f32_e32 v140, v141, v140
	v_div_scale_f32 v137, vcc, 1.0, v232, 1.0
	v_mul_f32_e32 v138, v137, v135
	v_fma_f32 v136, -v134, v138, v137
	v_fmac_f32_e32 v138, v136, v135
	v_fma_f32 v134, -v134, v138, v137
	v_div_fmas_f32 v134, v134, v135, v138
	v_div_fixup_f32 v232, v134, v232, 1.0
	v_div_scale_f32 v165, vcc, 1.0, v233, 1.0
	v_mul_f32_e32 v166, v165, v140
	v_fma_f32 v141, -v139, v166, v165
	v_fmac_f32_e32 v166, v141, v140
	v_fma_f32 v139, -v139, v166, v165
	v_div_fmas_f32 v139, v139, v140, v166
	v_div_fixup_f32 v233, v139, v233, 1.0
	global_store_dwordx4 v[186:187], v[230:233], off offset:576
	v_add_f32_e32 v226, v62, v210
	v_add_f32_e32 v227, v63, v211
	v_add_f32_e32 v228, v64, v212
	v_add_f32_e32 v229, v65, v213
	v_mul_f32_e32 v226, 0xbfb8aa3b, v226
	v_mul_f32_e32 v227, 0xbfb8aa3b, v227
	v_mul_f32_e32 v228, 0xbfb8aa3b, v228
	v_mul_f32_e32 v229, 0xbfb8aa3b, v229
	v_exp_f32_e32 v226, v226
	v_exp_f32_e32 v227, v227
	v_exp_f32_e32 v228, v228
	v_exp_f32_e32 v229, v229
	v_add_f32_e32 v226, 1.0, v226
	v_add_f32_e32 v227, 1.0, v227
	v_add_f32_e32 v228, 1.0, v228
	v_add_f32_e32 v229, 1.0, v229
	v_div_scale_f32 v134, s[2:3], v226, v226, 1.0
	v_div_scale_f32 v139, s[2:3], v227, v227, 1.0
	v_rcp_f32_e32 v135, v134
	v_rcp_f32_e32 v140, v139
	v_fma_f32 v136, -v134, v135, 1.0
	v_fma_f32 v141, -v139, v140, 1.0
	v_fmac_f32_e32 v135, v136, v135
	v_fmac_f32_e32 v140, v141, v140
	v_div_scale_f32 v137, vcc, 1.0, v226, 1.0
	v_mul_f32_e32 v138, v137, v135
	v_fma_f32 v136, -v134, v138, v137
	v_fmac_f32_e32 v138, v136, v135
	v_fma_f32 v134, -v134, v138, v137
	v_div_fmas_f32 v134, v134, v135, v138
	v_div_fixup_f32 v226, v134, v226, 1.0
	v_div_scale_f32 v165, vcc, 1.0, v227, 1.0
	v_mul_f32_e32 v166, v165, v140
	v_fma_f32 v141, -v139, v166, v165
	v_fmac_f32_e32 v166, v141, v140
	v_fma_f32 v139, -v139, v166, v165
	v_div_fmas_f32 v139, v139, v140, v166
	v_div_fixup_f32 v227, v139, v227, 1.0
	v_div_scale_f32 v134, s[2:3], v228, v228, 1.0
	v_div_scale_f32 v139, s[2:3], v229, v229, 1.0
	v_rcp_f32_e32 v135, v134
	v_rcp_f32_e32 v140, v139
	v_fma_f32 v136, -v134, v135, 1.0
	v_fma_f32 v141, -v139, v140, 1.0
	v_fmac_f32_e32 v135, v136, v135
	v_fmac_f32_e32 v140, v141, v140
	v_div_scale_f32 v137, vcc, 1.0, v228, 1.0
	v_mul_f32_e32 v138, v137, v135
	v_fma_f32 v136, -v134, v138, v137
	v_fmac_f32_e32 v138, v136, v135
	v_fma_f32 v134, -v134, v138, v137
	v_div_fmas_f32 v134, v134, v135, v138
	v_div_fixup_f32 v228, v134, v228, 1.0
	v_div_scale_f32 v165, vcc, 1.0, v229, 1.0
	v_mul_f32_e32 v166, v165, v140
	v_fma_f32 v141, -v139, v166, v165
	v_fmac_f32_e32 v166, v141, v140
	v_fma_f32 v139, -v139, v166, v165
	v_div_fmas_f32 v139, v139, v140, v166
	v_div_fixup_f32 v229, v139, v229, 1.0
	global_store_dwordx4 v[188:189], v[226:229], off
	v_add_f32_e32 v230, v58, v214
	v_add_f32_e32 v231, v59, v215
	v_add_f32_e32 v232, v60, v216
	v_add_f32_e32 v233, v61, v217
	v_mul_f32_e32 v230, 0xbfb8aa3b, v230
	v_mul_f32_e32 v231, 0xbfb8aa3b, v231
	v_mul_f32_e32 v232, 0xbfb8aa3b, v232
	v_mul_f32_e32 v233, 0xbfb8aa3b, v233
	v_exp_f32_e32 v230, v230
	v_exp_f32_e32 v231, v231
	v_exp_f32_e32 v232, v232
	v_exp_f32_e32 v233, v233
	v_add_f32_e32 v230, 1.0, v230
	v_add_f32_e32 v231, 1.0, v231
	v_add_f32_e32 v232, 1.0, v232
	v_add_f32_e32 v233, 1.0, v233
	v_div_scale_f32 v134, s[2:3], v230, v230, 1.0
	v_div_scale_f32 v139, s[2:3], v231, v231, 1.0
	v_rcp_f32_e32 v135, v134
	v_rcp_f32_e32 v140, v139
	v_fma_f32 v136, -v134, v135, 1.0
	v_fma_f32 v141, -v139, v140, 1.0
	v_fmac_f32_e32 v135, v136, v135
	v_fmac_f32_e32 v140, v141, v140
	v_div_scale_f32 v137, vcc, 1.0, v230, 1.0
	v_mul_f32_e32 v138, v137, v135
	v_fma_f32 v136, -v134, v138, v137
	v_fmac_f32_e32 v138, v136, v135
	v_fma_f32 v134, -v134, v138, v137
	v_div_fmas_f32 v134, v134, v135, v138
	v_div_fixup_f32 v230, v134, v230, 1.0
	v_div_scale_f32 v165, vcc, 1.0, v231, 1.0
	v_mul_f32_e32 v166, v165, v140
	v_fma_f32 v141, -v139, v166, v165
	v_fmac_f32_e32 v166, v141, v140
	v_fma_f32 v139, -v139, v166, v165
	v_div_fmas_f32 v139, v139, v140, v166
	v_div_fixup_f32 v231, v139, v231, 1.0
	v_div_scale_f32 v134, s[2:3], v232, v232, 1.0
	v_div_scale_f32 v139, s[2:3], v233, v233, 1.0
	v_rcp_f32_e32 v135, v134
	v_rcp_f32_e32 v140, v139
	v_fma_f32 v136, -v134, v135, 1.0
	v_fma_f32 v141, -v139, v140, 1.0
	v_fmac_f32_e32 v135, v136, v135
	v_fmac_f32_e32 v140, v141, v140
	v_div_scale_f32 v137, vcc, 1.0, v232, 1.0
	v_mul_f32_e32 v138, v137, v135
	v_fma_f32 v136, -v134, v138, v137
	v_fmac_f32_e32 v138, v136, v135
	v_fma_f32 v134, -v134, v138, v137
	v_div_fmas_f32 v134, v134, v135, v138
	v_div_fixup_f32 v232, v134, v232, 1.0
	v_div_scale_f32 v165, vcc, 1.0, v233, 1.0
	v_mul_f32_e32 v166, v165, v140
	v_fma_f32 v141, -v139, v166, v165
	v_fmac_f32_e32 v166, v141, v140
	v_fma_f32 v139, -v139, v166, v165
	v_div_fmas_f32 v139, v139, v140, v166
	v_div_fixup_f32 v233, v139, v233, 1.0
	global_store_dwordx4 v[188:189], v[230:233], off offset:64
	v_add_f32_e32 v226, v54, v218
	v_add_f32_e32 v227, v55, v219
	v_add_f32_e32 v228, v56, v220
	v_add_f32_e32 v229, v57, v221
	v_mul_f32_e32 v226, 0xbfb8aa3b, v226
	v_mul_f32_e32 v227, 0xbfb8aa3b, v227
	v_mul_f32_e32 v228, 0xbfb8aa3b, v228
	v_mul_f32_e32 v229, 0xbfb8aa3b, v229
	v_exp_f32_e32 v226, v226
	v_exp_f32_e32 v227, v227
	v_exp_f32_e32 v228, v228
	v_exp_f32_e32 v229, v229
	v_add_f32_e32 v226, 1.0, v226
	v_add_f32_e32 v227, 1.0, v227
	v_add_f32_e32 v228, 1.0, v228
	v_add_f32_e32 v229, 1.0, v229
	v_div_scale_f32 v134, s[2:3], v226, v226, 1.0
	v_div_scale_f32 v139, s[2:3], v227, v227, 1.0
	v_rcp_f32_e32 v135, v134
	v_rcp_f32_e32 v140, v139
	v_fma_f32 v136, -v134, v135, 1.0
	v_fma_f32 v141, -v139, v140, 1.0
	v_fmac_f32_e32 v135, v136, v135
	v_fmac_f32_e32 v140, v141, v140
	v_div_scale_f32 v137, vcc, 1.0, v226, 1.0
	v_mul_f32_e32 v138, v137, v135
	v_fma_f32 v136, -v134, v138, v137
	v_fmac_f32_e32 v138, v136, v135
	v_fma_f32 v134, -v134, v138, v137
	v_div_fmas_f32 v134, v134, v135, v138
	v_div_fixup_f32 v226, v134, v226, 1.0
	v_div_scale_f32 v165, vcc, 1.0, v227, 1.0
	v_mul_f32_e32 v166, v165, v140
	v_fma_f32 v141, -v139, v166, v165
	v_fmac_f32_e32 v166, v141, v140
	v_fma_f32 v139, -v139, v166, v165
	v_div_fmas_f32 v139, v139, v140, v166
	v_div_fixup_f32 v227, v139, v227, 1.0
	v_div_scale_f32 v134, s[2:3], v228, v228, 1.0
	v_div_scale_f32 v139, s[2:3], v229, v229, 1.0
	v_rcp_f32_e32 v135, v134
	v_rcp_f32_e32 v140, v139
	v_fma_f32 v136, -v134, v135, 1.0
	v_fma_f32 v141, -v139, v140, 1.0
	v_fmac_f32_e32 v135, v136, v135
	v_fmac_f32_e32 v140, v141, v140
	v_div_scale_f32 v137, vcc, 1.0, v228, 1.0
	v_mul_f32_e32 v138, v137, v135
	v_fma_f32 v136, -v134, v138, v137
	v_fmac_f32_e32 v138, v136, v135
	v_fma_f32 v134, -v134, v138, v137
	v_div_fmas_f32 v134, v134, v135, v138
	v_div_fixup_f32 v228, v134, v228, 1.0
	v_div_scale_f32 v165, vcc, 1.0, v229, 1.0
	v_mul_f32_e32 v166, v165, v140
	v_fma_f32 v141, -v139, v166, v165
	v_fmac_f32_e32 v166, v141, v140
	v_fma_f32 v139, -v139, v166, v165
	v_div_fmas_f32 v139, v139, v140, v166
	v_div_fixup_f32 v229, v139, v229, 1.0
	global_store_dwordx4 v[188:189], v[226:229], off offset:512
	v_add_f32_e32 v230, v50, v222
	v_add_f32_e32 v231, v51, v223
	v_add_f32_e32 v232, v52, v224
	v_add_f32_e32 v233, v53, v225
	v_mul_f32_e32 v230, 0xbfb8aa3b, v230
	v_mul_f32_e32 v231, 0xbfb8aa3b, v231
	v_mul_f32_e32 v232, 0xbfb8aa3b, v232
	v_mul_f32_e32 v233, 0xbfb8aa3b, v233
	v_exp_f32_e32 v230, v230
	v_exp_f32_e32 v231, v231
	v_exp_f32_e32 v232, v232
	v_exp_f32_e32 v233, v233
	v_add_f32_e32 v230, 1.0, v230
	v_add_f32_e32 v231, 1.0, v231
	v_add_f32_e32 v232, 1.0, v232
	v_add_f32_e32 v233, 1.0, v233
	v_div_scale_f32 v134, s[2:3], v230, v230, 1.0
	v_div_scale_f32 v139, s[2:3], v231, v231, 1.0
	v_rcp_f32_e32 v135, v134
	v_rcp_f32_e32 v140, v139
	v_fma_f32 v136, -v134, v135, 1.0
	v_fma_f32 v141, -v139, v140, 1.0
	v_fmac_f32_e32 v135, v136, v135
	v_fmac_f32_e32 v140, v141, v140
	v_div_scale_f32 v137, vcc, 1.0, v230, 1.0
	v_mul_f32_e32 v138, v137, v135
	v_fma_f32 v136, -v134, v138, v137
	v_fmac_f32_e32 v138, v136, v135
	v_fma_f32 v134, -v134, v138, v137
	v_div_fmas_f32 v134, v134, v135, v138
	v_div_fixup_f32 v230, v134, v230, 1.0
	v_div_scale_f32 v165, vcc, 1.0, v231, 1.0
	v_mul_f32_e32 v166, v165, v140
	v_fma_f32 v141, -v139, v166, v165
	v_fmac_f32_e32 v166, v141, v140
	v_fma_f32 v139, -v139, v166, v165
	v_div_fmas_f32 v139, v139, v140, v166
	v_div_fixup_f32 v231, v139, v231, 1.0
	v_div_scale_f32 v134, s[2:3], v232, v232, 1.0
	v_div_scale_f32 v139, s[2:3], v233, v233, 1.0
	v_rcp_f32_e32 v135, v134
	v_rcp_f32_e32 v140, v139
	v_fma_f32 v136, -v134, v135, 1.0
	v_fma_f32 v141, -v139, v140, 1.0
	v_fmac_f32_e32 v135, v136, v135
	v_fmac_f32_e32 v140, v141, v140
	v_div_scale_f32 v137, vcc, 1.0, v232, 1.0
	v_mul_f32_e32 v138, v137, v135
	v_fma_f32 v136, -v134, v138, v137
	v_fmac_f32_e32 v138, v136, v135
	v_fma_f32 v134, -v134, v138, v137
	v_div_fmas_f32 v134, v134, v135, v138
	v_div_fixup_f32 v232, v134, v232, 1.0
	v_div_scale_f32 v165, vcc, 1.0, v233, 1.0
	v_mul_f32_e32 v166, v165, v140
	v_fma_f32 v141, -v139, v166, v165
	v_fmac_f32_e32 v166, v141, v140
	v_fma_f32 v139, -v139, v166, v165
	v_div_fmas_f32 v139, v139, v140, v166
	v_div_fixup_f32 v233, v139, v233, 1.0
	global_store_dwordx4 v[188:189], v[230:233], off offset:576
	v_add_f32_e32 v226, v46, v210
	v_add_f32_e32 v227, v47, v211
	v_add_f32_e32 v228, v48, v212
	v_add_f32_e32 v229, v49, v213
	v_mul_f32_e32 v226, 0xbfb8aa3b, v226
	v_mul_f32_e32 v227, 0xbfb8aa3b, v227
	v_mul_f32_e32 v228, 0xbfb8aa3b, v228
	v_mul_f32_e32 v229, 0xbfb8aa3b, v229
	v_exp_f32_e32 v226, v226
	v_exp_f32_e32 v227, v227
	v_exp_f32_e32 v228, v228
	v_exp_f32_e32 v229, v229
	v_add_f32_e32 v226, 1.0, v226
	v_add_f32_e32 v227, 1.0, v227
	v_add_f32_e32 v228, 1.0, v228
	v_add_f32_e32 v229, 1.0, v229
	v_div_scale_f32 v134, s[2:3], v226, v226, 1.0
	v_div_scale_f32 v139, s[2:3], v227, v227, 1.0
	v_rcp_f32_e32 v135, v134
	v_rcp_f32_e32 v140, v139
	v_fma_f32 v136, -v134, v135, 1.0
	v_fma_f32 v141, -v139, v140, 1.0
	v_fmac_f32_e32 v135, v136, v135
	v_fmac_f32_e32 v140, v141, v140
	v_div_scale_f32 v137, vcc, 1.0, v226, 1.0
	v_mul_f32_e32 v138, v137, v135
	v_fma_f32 v136, -v134, v138, v137
	v_fmac_f32_e32 v138, v136, v135
	v_fma_f32 v134, -v134, v138, v137
	v_div_fmas_f32 v134, v134, v135, v138
	v_div_fixup_f32 v226, v134, v226, 1.0
	v_div_scale_f32 v165, vcc, 1.0, v227, 1.0
	v_mul_f32_e32 v166, v165, v140
	v_fma_f32 v141, -v139, v166, v165
	v_fmac_f32_e32 v166, v141, v140
	v_fma_f32 v139, -v139, v166, v165
	v_div_fmas_f32 v139, v139, v140, v166
	v_div_fixup_f32 v227, v139, v227, 1.0
	v_div_scale_f32 v134, s[2:3], v228, v228, 1.0
	v_div_scale_f32 v139, s[2:3], v229, v229, 1.0
	v_rcp_f32_e32 v135, v134
	v_rcp_f32_e32 v140, v139
	v_fma_f32 v136, -v134, v135, 1.0
	v_fma_f32 v141, -v139, v140, 1.0
	v_fmac_f32_e32 v135, v136, v135
	v_fmac_f32_e32 v140, v141, v140
	v_div_scale_f32 v137, vcc, 1.0, v228, 1.0
	v_mul_f32_e32 v138, v137, v135
	v_fma_f32 v136, -v134, v138, v137
	v_fmac_f32_e32 v138, v136, v135
	v_fma_f32 v134, -v134, v138, v137
	v_div_fmas_f32 v134, v134, v135, v138
	v_div_fixup_f32 v228, v134, v228, 1.0
	v_div_scale_f32 v165, vcc, 1.0, v229, 1.0
	v_mul_f32_e32 v166, v165, v140
	v_fma_f32 v141, -v139, v166, v165
	v_fmac_f32_e32 v166, v141, v140
	v_fma_f32 v139, -v139, v166, v165
	v_div_fmas_f32 v139, v139, v140, v166
	v_div_fixup_f32 v229, v139, v229, 1.0
	global_store_dwordx4 v[190:191], v[226:229], off
	v_add_f32_e32 v230, v42, v214
	v_add_f32_e32 v231, v43, v215
	v_add_f32_e32 v232, v44, v216
	v_add_f32_e32 v233, v45, v217
	v_mul_f32_e32 v230, 0xbfb8aa3b, v230
	v_mul_f32_e32 v231, 0xbfb8aa3b, v231
	v_mul_f32_e32 v232, 0xbfb8aa3b, v232
	v_mul_f32_e32 v233, 0xbfb8aa3b, v233
	v_exp_f32_e32 v230, v230
	v_exp_f32_e32 v231, v231
	v_exp_f32_e32 v232, v232
	v_exp_f32_e32 v233, v233
	v_add_f32_e32 v230, 1.0, v230
	v_add_f32_e32 v231, 1.0, v231
	v_add_f32_e32 v232, 1.0, v232
	v_add_f32_e32 v233, 1.0, v233
	v_div_scale_f32 v134, s[2:3], v230, v230, 1.0
	v_div_scale_f32 v139, s[2:3], v231, v231, 1.0
	v_rcp_f32_e32 v135, v134
	v_rcp_f32_e32 v140, v139
	v_fma_f32 v136, -v134, v135, 1.0
	v_fma_f32 v141, -v139, v140, 1.0
	v_fmac_f32_e32 v135, v136, v135
	v_fmac_f32_e32 v140, v141, v140
	v_div_scale_f32 v137, vcc, 1.0, v230, 1.0
	v_mul_f32_e32 v138, v137, v135
	v_fma_f32 v136, -v134, v138, v137
	v_fmac_f32_e32 v138, v136, v135
	v_fma_f32 v134, -v134, v138, v137
	v_div_fmas_f32 v134, v134, v135, v138
	v_div_fixup_f32 v230, v134, v230, 1.0
	v_div_scale_f32 v165, vcc, 1.0, v231, 1.0
	v_mul_f32_e32 v166, v165, v140
	v_fma_f32 v141, -v139, v166, v165
	v_fmac_f32_e32 v166, v141, v140
	v_fma_f32 v139, -v139, v166, v165
	v_div_fmas_f32 v139, v139, v140, v166
	v_div_fixup_f32 v231, v139, v231, 1.0
	v_div_scale_f32 v134, s[2:3], v232, v232, 1.0
	v_div_scale_f32 v139, s[2:3], v233, v233, 1.0
	v_rcp_f32_e32 v135, v134
	v_rcp_f32_e32 v140, v139
	v_fma_f32 v136, -v134, v135, 1.0
	v_fma_f32 v141, -v139, v140, 1.0
	v_fmac_f32_e32 v135, v136, v135
	v_fmac_f32_e32 v140, v141, v140
	v_div_scale_f32 v137, vcc, 1.0, v232, 1.0
	v_mul_f32_e32 v138, v137, v135
	v_fma_f32 v136, -v134, v138, v137
	v_fmac_f32_e32 v138, v136, v135
	v_fma_f32 v134, -v134, v138, v137
	v_div_fmas_f32 v134, v134, v135, v138
	v_div_fixup_f32 v232, v134, v232, 1.0
	v_div_scale_f32 v165, vcc, 1.0, v233, 1.0
	v_mul_f32_e32 v166, v165, v140
	v_fma_f32 v141, -v139, v166, v165
	v_fmac_f32_e32 v166, v141, v140
	v_fma_f32 v139, -v139, v166, v165
	v_div_fmas_f32 v139, v139, v140, v166
	v_div_fixup_f32 v233, v139, v233, 1.0
	global_store_dwordx4 v[190:191], v[230:233], off offset:64
	v_add_f32_e32 v226, v38, v218
	v_add_f32_e32 v227, v39, v219
	v_add_f32_e32 v228, v40, v220
	v_add_f32_e32 v229, v41, v221
	v_mul_f32_e32 v226, 0xbfb8aa3b, v226
	v_mul_f32_e32 v227, 0xbfb8aa3b, v227
	v_mul_f32_e32 v228, 0xbfb8aa3b, v228
	v_mul_f32_e32 v229, 0xbfb8aa3b, v229
	v_exp_f32_e32 v226, v226
	v_exp_f32_e32 v227, v227
	v_exp_f32_e32 v228, v228
	v_exp_f32_e32 v229, v229
	v_add_f32_e32 v226, 1.0, v226
	v_add_f32_e32 v227, 1.0, v227
	v_add_f32_e32 v228, 1.0, v228
	v_add_f32_e32 v229, 1.0, v229
	v_div_scale_f32 v134, s[2:3], v226, v226, 1.0
	v_div_scale_f32 v139, s[2:3], v227, v227, 1.0
	v_rcp_f32_e32 v135, v134
	v_rcp_f32_e32 v140, v139
	v_fma_f32 v136, -v134, v135, 1.0
	v_fma_f32 v141, -v139, v140, 1.0
	v_fmac_f32_e32 v135, v136, v135
	v_fmac_f32_e32 v140, v141, v140
	v_div_scale_f32 v137, vcc, 1.0, v226, 1.0
	v_mul_f32_e32 v138, v137, v135
	v_fma_f32 v136, -v134, v138, v137
	v_fmac_f32_e32 v138, v136, v135
	v_fma_f32 v134, -v134, v138, v137
	v_div_fmas_f32 v134, v134, v135, v138
	v_div_fixup_f32 v226, v134, v226, 1.0
	v_div_scale_f32 v165, vcc, 1.0, v227, 1.0
	v_mul_f32_e32 v166, v165, v140
	v_fma_f32 v141, -v139, v166, v165
	v_fmac_f32_e32 v166, v141, v140
	v_fma_f32 v139, -v139, v166, v165
	v_div_fmas_f32 v139, v139, v140, v166
	v_div_fixup_f32 v227, v139, v227, 1.0
	v_div_scale_f32 v134, s[2:3], v228, v228, 1.0
	v_div_scale_f32 v139, s[2:3], v229, v229, 1.0
	v_rcp_f32_e32 v135, v134
	v_rcp_f32_e32 v140, v139
	v_fma_f32 v136, -v134, v135, 1.0
	v_fma_f32 v141, -v139, v140, 1.0
	v_fmac_f32_e32 v135, v136, v135
	v_fmac_f32_e32 v140, v141, v140
	v_div_scale_f32 v137, vcc, 1.0, v228, 1.0
	v_mul_f32_e32 v138, v137, v135
	v_fma_f32 v136, -v134, v138, v137
	v_fmac_f32_e32 v138, v136, v135
	v_fma_f32 v134, -v134, v138, v137
	v_div_fmas_f32 v134, v134, v135, v138
	v_div_fixup_f32 v228, v134, v228, 1.0
	v_div_scale_f32 v165, vcc, 1.0, v229, 1.0
	v_mul_f32_e32 v166, v165, v140
	v_fma_f32 v141, -v139, v166, v165
	v_fmac_f32_e32 v166, v141, v140
	v_fma_f32 v139, -v139, v166, v165
	v_div_fmas_f32 v139, v139, v140, v166
	v_div_fixup_f32 v229, v139, v229, 1.0
	global_store_dwordx4 v[190:191], v[226:229], off offset:512
	v_add_f32_e32 v230, v34, v222
	v_add_f32_e32 v231, v35, v223
	v_add_f32_e32 v232, v36, v224
	v_add_f32_e32 v233, v37, v225
	v_mul_f32_e32 v230, 0xbfb8aa3b, v230
	v_mul_f32_e32 v231, 0xbfb8aa3b, v231
	v_mul_f32_e32 v232, 0xbfb8aa3b, v232
	v_mul_f32_e32 v233, 0xbfb8aa3b, v233
	v_exp_f32_e32 v230, v230
	v_exp_f32_e32 v231, v231
	v_exp_f32_e32 v232, v232
	v_exp_f32_e32 v233, v233
	v_add_f32_e32 v230, 1.0, v230
	v_add_f32_e32 v231, 1.0, v231
	v_add_f32_e32 v232, 1.0, v232
	v_add_f32_e32 v233, 1.0, v233
	v_div_scale_f32 v134, s[2:3], v230, v230, 1.0
	v_div_scale_f32 v139, s[2:3], v231, v231, 1.0
	v_rcp_f32_e32 v135, v134
	v_rcp_f32_e32 v140, v139
	v_fma_f32 v136, -v134, v135, 1.0
	v_fma_f32 v141, -v139, v140, 1.0
	v_fmac_f32_e32 v135, v136, v135
	v_fmac_f32_e32 v140, v141, v140
	v_div_scale_f32 v137, vcc, 1.0, v230, 1.0
	v_mul_f32_e32 v138, v137, v135
	v_fma_f32 v136, -v134, v138, v137
	v_fmac_f32_e32 v138, v136, v135
	v_fma_f32 v134, -v134, v138, v137
	v_div_fmas_f32 v134, v134, v135, v138
	v_div_fixup_f32 v230, v134, v230, 1.0
	v_div_scale_f32 v165, vcc, 1.0, v231, 1.0
	v_mul_f32_e32 v166, v165, v140
	v_fma_f32 v141, -v139, v166, v165
	v_fmac_f32_e32 v166, v141, v140
	v_fma_f32 v139, -v139, v166, v165
	v_div_fmas_f32 v139, v139, v140, v166
	v_div_fixup_f32 v231, v139, v231, 1.0
	v_div_scale_f32 v134, s[2:3], v232, v232, 1.0
	v_div_scale_f32 v139, s[2:3], v233, v233, 1.0
	v_rcp_f32_e32 v135, v134
	v_rcp_f32_e32 v140, v139
	v_fma_f32 v136, -v134, v135, 1.0
	v_fma_f32 v141, -v139, v140, 1.0
	v_fmac_f32_e32 v135, v136, v135
	v_fmac_f32_e32 v140, v141, v140
	v_div_scale_f32 v137, vcc, 1.0, v232, 1.0
	v_mul_f32_e32 v138, v137, v135
	v_fma_f32 v136, -v134, v138, v137
	v_fmac_f32_e32 v138, v136, v135
	v_fma_f32 v134, -v134, v138, v137
	v_div_fmas_f32 v134, v134, v135, v138
	v_div_fixup_f32 v232, v134, v232, 1.0
	v_div_scale_f32 v165, vcc, 1.0, v233, 1.0
	v_mul_f32_e32 v166, v165, v140
	v_fma_f32 v141, -v139, v166, v165
	v_fmac_f32_e32 v166, v141, v140
	v_fma_f32 v139, -v139, v166, v165
	v_div_fmas_f32 v139, v139, v140, v166
	v_div_fixup_f32 v233, v139, v233, 1.0
	global_store_dwordx4 v[190:191], v[230:233], off offset:576
	v_add_f32_e32 v226, v30, v210
	v_add_f32_e32 v227, v31, v211
	v_add_f32_e32 v228, v32, v212
	v_add_f32_e32 v229, v33, v213
	v_mul_f32_e32 v226, 0xbfb8aa3b, v226
	v_mul_f32_e32 v227, 0xbfb8aa3b, v227
	v_mul_f32_e32 v228, 0xbfb8aa3b, v228
	v_mul_f32_e32 v229, 0xbfb8aa3b, v229
	v_exp_f32_e32 v226, v226
	v_exp_f32_e32 v227, v227
	v_exp_f32_e32 v228, v228
	v_exp_f32_e32 v229, v229
	v_add_f32_e32 v226, 1.0, v226
	v_add_f32_e32 v227, 1.0, v227
	v_add_f32_e32 v228, 1.0, v228
	v_add_f32_e32 v229, 1.0, v229
	v_div_scale_f32 v134, s[2:3], v226, v226, 1.0
	v_div_scale_f32 v139, s[2:3], v227, v227, 1.0
	v_rcp_f32_e32 v135, v134
	v_rcp_f32_e32 v140, v139
	v_fma_f32 v136, -v134, v135, 1.0
	v_fma_f32 v141, -v139, v140, 1.0
	v_fmac_f32_e32 v135, v136, v135
	v_fmac_f32_e32 v140, v141, v140
	v_div_scale_f32 v137, vcc, 1.0, v226, 1.0
	v_mul_f32_e32 v138, v137, v135
	v_fma_f32 v136, -v134, v138, v137
	v_fmac_f32_e32 v138, v136, v135
	v_fma_f32 v134, -v134, v138, v137
	v_div_fmas_f32 v134, v134, v135, v138
	v_div_fixup_f32 v226, v134, v226, 1.0
	v_div_scale_f32 v165, vcc, 1.0, v227, 1.0
	v_mul_f32_e32 v166, v165, v140
	v_fma_f32 v141, -v139, v166, v165
	v_fmac_f32_e32 v166, v141, v140
	v_fma_f32 v139, -v139, v166, v165
	v_div_fmas_f32 v139, v139, v140, v166
	v_div_fixup_f32 v227, v139, v227, 1.0
	v_div_scale_f32 v134, s[2:3], v228, v228, 1.0
	v_div_scale_f32 v139, s[2:3], v229, v229, 1.0
	v_rcp_f32_e32 v135, v134
	v_rcp_f32_e32 v140, v139
	v_fma_f32 v136, -v134, v135, 1.0
	v_fma_f32 v141, -v139, v140, 1.0
	v_fmac_f32_e32 v135, v136, v135
	v_fmac_f32_e32 v140, v141, v140
	v_div_scale_f32 v137, vcc, 1.0, v228, 1.0
	v_mul_f32_e32 v138, v137, v135
	v_fma_f32 v136, -v134, v138, v137
	v_fmac_f32_e32 v138, v136, v135
	v_fma_f32 v134, -v134, v138, v137
	v_div_fmas_f32 v134, v134, v135, v138
	v_div_fixup_f32 v228, v134, v228, 1.0
	v_div_scale_f32 v165, vcc, 1.0, v229, 1.0
	v_mul_f32_e32 v166, v165, v140
	v_fma_f32 v141, -v139, v166, v165
	v_fmac_f32_e32 v166, v141, v140
	v_fma_f32 v139, -v139, v166, v165
	v_div_fmas_f32 v139, v139, v140, v166
	v_div_fixup_f32 v229, v139, v229, 1.0
	global_store_dwordx4 v[192:193], v[226:229], off
	v_add_f32_e32 v230, v24, v214
	v_add_f32_e32 v231, v25, v215
	v_add_f32_e32 v232, v26, v216
	v_add_f32_e32 v233, v27, v217
	v_mul_f32_e32 v230, 0xbfb8aa3b, v230
	v_mul_f32_e32 v231, 0xbfb8aa3b, v231
	v_mul_f32_e32 v232, 0xbfb8aa3b, v232
	v_mul_f32_e32 v233, 0xbfb8aa3b, v233
	v_exp_f32_e32 v230, v230
	v_exp_f32_e32 v231, v231
	v_exp_f32_e32 v232, v232
	v_exp_f32_e32 v233, v233
	v_add_f32_e32 v230, 1.0, v230
	v_add_f32_e32 v231, 1.0, v231
	v_add_f32_e32 v232, 1.0, v232
	v_add_f32_e32 v233, 1.0, v233
	v_div_scale_f32 v134, s[2:3], v230, v230, 1.0
	v_div_scale_f32 v139, s[2:3], v231, v231, 1.0
	v_rcp_f32_e32 v135, v134
	v_rcp_f32_e32 v140, v139
	v_fma_f32 v136, -v134, v135, 1.0
	v_fma_f32 v141, -v139, v140, 1.0
	v_fmac_f32_e32 v135, v136, v135
	v_fmac_f32_e32 v140, v141, v140
	v_div_scale_f32 v137, vcc, 1.0, v230, 1.0
	v_mul_f32_e32 v138, v137, v135
	v_fma_f32 v136, -v134, v138, v137
	v_fmac_f32_e32 v138, v136, v135
	v_fma_f32 v134, -v134, v138, v137
	v_div_fmas_f32 v134, v134, v135, v138
	v_div_fixup_f32 v230, v134, v230, 1.0
	v_div_scale_f32 v165, vcc, 1.0, v231, 1.0
	v_mul_f32_e32 v166, v165, v140
	v_fma_f32 v141, -v139, v166, v165
	v_fmac_f32_e32 v166, v141, v140
	v_fma_f32 v139, -v139, v166, v165
	v_div_fmas_f32 v139, v139, v140, v166
	v_div_fixup_f32 v231, v139, v231, 1.0
	v_div_scale_f32 v134, s[2:3], v232, v232, 1.0
	v_div_scale_f32 v139, s[2:3], v233, v233, 1.0
	v_rcp_f32_e32 v135, v134
	v_rcp_f32_e32 v140, v139
	v_fma_f32 v136, -v134, v135, 1.0
	v_fma_f32 v141, -v139, v140, 1.0
	v_fmac_f32_e32 v135, v136, v135
	v_fmac_f32_e32 v140, v141, v140
	v_div_scale_f32 v137, vcc, 1.0, v232, 1.0
	v_mul_f32_e32 v138, v137, v135
	v_fma_f32 v136, -v134, v138, v137
	v_fmac_f32_e32 v138, v136, v135
	v_fma_f32 v134, -v134, v138, v137
	v_div_fmas_f32 v134, v134, v135, v138
	v_div_fixup_f32 v232, v134, v232, 1.0
	v_div_scale_f32 v165, vcc, 1.0, v233, 1.0
	v_mul_f32_e32 v166, v165, v140
	v_fma_f32 v141, -v139, v166, v165
	v_fmac_f32_e32 v166, v141, v140
	v_fma_f32 v139, -v139, v166, v165
	v_div_fmas_f32 v139, v139, v140, v166
	v_div_fixup_f32 v233, v139, v233, 1.0
	global_store_dwordx4 v[192:193], v[230:233], off offset:64
	v_add_f32_e32 v226, v20, v218
	v_add_f32_e32 v227, v21, v219
	v_add_f32_e32 v228, v22, v220
	v_add_f32_e32 v229, v23, v221
	v_mul_f32_e32 v226, 0xbfb8aa3b, v226
	v_mul_f32_e32 v227, 0xbfb8aa3b, v227
	v_mul_f32_e32 v228, 0xbfb8aa3b, v228
	v_mul_f32_e32 v229, 0xbfb8aa3b, v229
	v_exp_f32_e32 v226, v226
	v_exp_f32_e32 v227, v227
	v_exp_f32_e32 v228, v228
	v_exp_f32_e32 v229, v229
	v_add_f32_e32 v226, 1.0, v226
	v_add_f32_e32 v227, 1.0, v227
	v_add_f32_e32 v228, 1.0, v228
	v_add_f32_e32 v229, 1.0, v229
	v_div_scale_f32 v134, s[2:3], v226, v226, 1.0
	v_div_scale_f32 v139, s[2:3], v227, v227, 1.0
	v_rcp_f32_e32 v135, v134
	v_rcp_f32_e32 v140, v139
	v_fma_f32 v136, -v134, v135, 1.0
	v_fma_f32 v141, -v139, v140, 1.0
	v_fmac_f32_e32 v135, v136, v135
	v_fmac_f32_e32 v140, v141, v140
	v_div_scale_f32 v137, vcc, 1.0, v226, 1.0
	v_mul_f32_e32 v138, v137, v135
	v_fma_f32 v136, -v134, v138, v137
	v_fmac_f32_e32 v138, v136, v135
	v_fma_f32 v134, -v134, v138, v137
	v_div_fmas_f32 v134, v134, v135, v138
	v_div_fixup_f32 v226, v134, v226, 1.0
	v_div_scale_f32 v165, vcc, 1.0, v227, 1.0
	v_mul_f32_e32 v166, v165, v140
	v_fma_f32 v141, -v139, v166, v165
	v_fmac_f32_e32 v166, v141, v140
	v_fma_f32 v139, -v139, v166, v165
	v_div_fmas_f32 v139, v139, v140, v166
	v_div_fixup_f32 v227, v139, v227, 1.0
	v_div_scale_f32 v134, s[2:3], v228, v228, 1.0
	v_div_scale_f32 v139, s[2:3], v229, v229, 1.0
	v_rcp_f32_e32 v135, v134
	v_rcp_f32_e32 v140, v139
	v_fma_f32 v136, -v134, v135, 1.0
	v_fma_f32 v141, -v139, v140, 1.0
	v_fmac_f32_e32 v135, v136, v135
	v_fmac_f32_e32 v140, v141, v140
	v_div_scale_f32 v137, vcc, 1.0, v228, 1.0
	v_mul_f32_e32 v138, v137, v135
	v_fma_f32 v136, -v134, v138, v137
	v_fmac_f32_e32 v138, v136, v135
	v_fma_f32 v134, -v134, v138, v137
	v_div_fmas_f32 v134, v134, v135, v138
	v_div_fixup_f32 v228, v134, v228, 1.0
	v_div_scale_f32 v165, vcc, 1.0, v229, 1.0
	v_mul_f32_e32 v166, v165, v140
	v_fma_f32 v141, -v139, v166, v165
	v_fmac_f32_e32 v166, v141, v140
	v_fma_f32 v139, -v139, v166, v165
	v_div_fmas_f32 v139, v139, v140, v166
	v_div_fixup_f32 v229, v139, v229, 1.0
	global_store_dwordx4 v[192:193], v[226:229], off offset:512
	v_add_f32_e32 v230, v16, v222
	v_add_f32_e32 v231, v17, v223
	v_add_f32_e32 v232, v18, v224
	v_add_f32_e32 v233, v19, v225
	v_mul_f32_e32 v230, 0xbfb8aa3b, v230
	v_mul_f32_e32 v231, 0xbfb8aa3b, v231
	v_mul_f32_e32 v232, 0xbfb8aa3b, v232
	v_mul_f32_e32 v233, 0xbfb8aa3b, v233
	v_exp_f32_e32 v230, v230
	v_exp_f32_e32 v231, v231
	v_exp_f32_e32 v232, v232
	v_exp_f32_e32 v233, v233
	v_add_f32_e32 v230, 1.0, v230
	v_add_f32_e32 v231, 1.0, v231
	v_add_f32_e32 v232, 1.0, v232
	v_add_f32_e32 v233, 1.0, v233
	v_div_scale_f32 v134, s[2:3], v230, v230, 1.0
	v_div_scale_f32 v139, s[2:3], v231, v231, 1.0
	v_rcp_f32_e32 v135, v134
	v_rcp_f32_e32 v140, v139
	v_fma_f32 v136, -v134, v135, 1.0
	v_fma_f32 v141, -v139, v140, 1.0
	v_fmac_f32_e32 v135, v136, v135
	v_fmac_f32_e32 v140, v141, v140
	v_div_scale_f32 v137, vcc, 1.0, v230, 1.0
	v_mul_f32_e32 v138, v137, v135
	v_fma_f32 v136, -v134, v138, v137
	v_fmac_f32_e32 v138, v136, v135
	v_fma_f32 v134, -v134, v138, v137
	v_div_fmas_f32 v134, v134, v135, v138
	v_div_fixup_f32 v230, v134, v230, 1.0
	v_div_scale_f32 v165, vcc, 1.0, v231, 1.0
	v_mul_f32_e32 v166, v165, v140
	v_fma_f32 v141, -v139, v166, v165
	v_fmac_f32_e32 v166, v141, v140
	v_fma_f32 v139, -v139, v166, v165
	v_div_fmas_f32 v139, v139, v140, v166
	v_div_fixup_f32 v231, v139, v231, 1.0
	v_div_scale_f32 v134, s[2:3], v232, v232, 1.0
	v_div_scale_f32 v139, s[2:3], v233, v233, 1.0
	v_rcp_f32_e32 v135, v134
	v_rcp_f32_e32 v140, v139
	v_fma_f32 v136, -v134, v135, 1.0
	v_fma_f32 v141, -v139, v140, 1.0
	v_fmac_f32_e32 v135, v136, v135
	v_fmac_f32_e32 v140, v141, v140
	v_div_scale_f32 v137, vcc, 1.0, v232, 1.0
	v_mul_f32_e32 v138, v137, v135
	v_fma_f32 v136, -v134, v138, v137
	v_fmac_f32_e32 v138, v136, v135
	v_fma_f32 v134, -v134, v138, v137
	v_div_fmas_f32 v134, v134, v135, v138
	v_div_fixup_f32 v232, v134, v232, 1.0
	v_div_scale_f32 v165, vcc, 1.0, v233, 1.0
	v_mul_f32_e32 v166, v165, v140
	v_fma_f32 v141, -v139, v166, v165
	v_fmac_f32_e32 v166, v141, v140
	v_fma_f32 v139, -v139, v166, v165
	v_div_fmas_f32 v139, v139, v140, v166
	v_div_fixup_f32 v233, v139, v233, 1.0
	global_store_dwordx4 v[192:193], v[230:233], off offset:576
	v_add_f32_e32 v226, v12, v210
	v_add_f32_e32 v227, v13, v211
	v_add_f32_e32 v228, v14, v212
	v_add_f32_e32 v229, v15, v213
	v_mul_f32_e32 v226, 0xbfb8aa3b, v226
	v_mul_f32_e32 v227, 0xbfb8aa3b, v227
	v_mul_f32_e32 v228, 0xbfb8aa3b, v228
	v_mul_f32_e32 v229, 0xbfb8aa3b, v229
	v_exp_f32_e32 v226, v226
	v_exp_f32_e32 v227, v227
	v_exp_f32_e32 v228, v228
	v_exp_f32_e32 v229, v229
	v_add_f32_e32 v226, 1.0, v226
	v_add_f32_e32 v227, 1.0, v227
	v_add_f32_e32 v228, 1.0, v228
	v_add_f32_e32 v229, 1.0, v229
	v_div_scale_f32 v134, s[2:3], v226, v226, 1.0
	v_div_scale_f32 v139, s[2:3], v227, v227, 1.0
	v_rcp_f32_e32 v135, v134
	v_rcp_f32_e32 v140, v139
	v_fma_f32 v136, -v134, v135, 1.0
	v_fma_f32 v141, -v139, v140, 1.0
	v_fmac_f32_e32 v135, v136, v135
	v_fmac_f32_e32 v140, v141, v140
	v_div_scale_f32 v137, vcc, 1.0, v226, 1.0
	v_mul_f32_e32 v138, v137, v135
	v_fma_f32 v136, -v134, v138, v137
	v_fmac_f32_e32 v138, v136, v135
	v_fma_f32 v134, -v134, v138, v137
	v_div_fmas_f32 v134, v134, v135, v138
	v_div_fixup_f32 v226, v134, v226, 1.0
	v_div_scale_f32 v165, vcc, 1.0, v227, 1.0
	v_mul_f32_e32 v166, v165, v140
	v_fma_f32 v141, -v139, v166, v165
	v_fmac_f32_e32 v166, v141, v140
	v_fma_f32 v139, -v139, v166, v165
	v_div_fmas_f32 v139, v139, v140, v166
	v_div_fixup_f32 v227, v139, v227, 1.0
	v_div_scale_f32 v134, s[2:3], v228, v228, 1.0
	v_div_scale_f32 v139, s[2:3], v229, v229, 1.0
	v_rcp_f32_e32 v135, v134
	v_rcp_f32_e32 v140, v139
	v_fma_f32 v136, -v134, v135, 1.0
	v_fma_f32 v141, -v139, v140, 1.0
	v_fmac_f32_e32 v135, v136, v135
	v_fmac_f32_e32 v140, v141, v140
	v_div_scale_f32 v137, vcc, 1.0, v228, 1.0
	v_mul_f32_e32 v138, v137, v135
	v_fma_f32 v136, -v134, v138, v137
	v_fmac_f32_e32 v138, v136, v135
	v_fma_f32 v134, -v134, v138, v137
	v_div_fmas_f32 v134, v134, v135, v138
	v_div_fixup_f32 v228, v134, v228, 1.0
	v_div_scale_f32 v165, vcc, 1.0, v229, 1.0
	v_mul_f32_e32 v166, v165, v140
	v_fma_f32 v141, -v139, v166, v165
	v_fmac_f32_e32 v166, v141, v140
	v_fma_f32 v139, -v139, v166, v165
	v_div_fmas_f32 v139, v139, v140, v166
	v_div_fixup_f32 v229, v139, v229, 1.0
	global_store_dwordx4 v[194:195], v[226:229], off
	v_add_f32_e32 v230, v8, v214
	v_add_f32_e32 v231, v9, v215
	v_add_f32_e32 v232, v10, v216
	v_add_f32_e32 v233, v11, v217
	v_mul_f32_e32 v230, 0xbfb8aa3b, v230
	v_mul_f32_e32 v231, 0xbfb8aa3b, v231
	v_mul_f32_e32 v232, 0xbfb8aa3b, v232
	v_mul_f32_e32 v233, 0xbfb8aa3b, v233
	v_exp_f32_e32 v230, v230
	v_exp_f32_e32 v231, v231
	v_exp_f32_e32 v232, v232
	v_exp_f32_e32 v233, v233
	v_add_f32_e32 v230, 1.0, v230
	v_add_f32_e32 v231, 1.0, v231
	v_add_f32_e32 v232, 1.0, v232
	v_add_f32_e32 v233, 1.0, v233
	v_div_scale_f32 v134, s[2:3], v230, v230, 1.0
	v_div_scale_f32 v139, s[2:3], v231, v231, 1.0
	v_rcp_f32_e32 v135, v134
	v_rcp_f32_e32 v140, v139
	v_fma_f32 v136, -v134, v135, 1.0
	v_fma_f32 v141, -v139, v140, 1.0
	v_fmac_f32_e32 v135, v136, v135
	v_fmac_f32_e32 v140, v141, v140
	v_div_scale_f32 v137, vcc, 1.0, v230, 1.0
	v_mul_f32_e32 v138, v137, v135
	v_fma_f32 v136, -v134, v138, v137
	v_fmac_f32_e32 v138, v136, v135
	v_fma_f32 v134, -v134, v138, v137
	v_div_fmas_f32 v134, v134, v135, v138
	v_div_fixup_f32 v230, v134, v230, 1.0
	v_div_scale_f32 v165, vcc, 1.0, v231, 1.0
	v_mul_f32_e32 v166, v165, v140
	v_fma_f32 v141, -v139, v166, v165
	v_fmac_f32_e32 v166, v141, v140
	v_fma_f32 v139, -v139, v166, v165
	v_div_fmas_f32 v139, v139, v140, v166
	v_div_fixup_f32 v231, v139, v231, 1.0
	v_div_scale_f32 v134, s[2:3], v232, v232, 1.0
	v_div_scale_f32 v139, s[2:3], v233, v233, 1.0
	v_rcp_f32_e32 v135, v134
	v_rcp_f32_e32 v140, v139
	v_fma_f32 v136, -v134, v135, 1.0
	v_fma_f32 v141, -v139, v140, 1.0
	v_fmac_f32_e32 v135, v136, v135
	v_fmac_f32_e32 v140, v141, v140
	v_div_scale_f32 v137, vcc, 1.0, v232, 1.0
	v_mul_f32_e32 v138, v137, v135
	v_fma_f32 v136, -v134, v138, v137
	v_fmac_f32_e32 v138, v136, v135
	v_fma_f32 v134, -v134, v138, v137
	v_div_fmas_f32 v134, v134, v135, v138
	v_div_fixup_f32 v232, v134, v232, 1.0
	v_div_scale_f32 v165, vcc, 1.0, v233, 1.0
	v_mul_f32_e32 v166, v165, v140
	v_fma_f32 v141, -v139, v166, v165
	v_fmac_f32_e32 v166, v141, v140
	v_fma_f32 v139, -v139, v166, v165
	v_div_fmas_f32 v139, v139, v140, v166
	v_div_fixup_f32 v233, v139, v233, 1.0
	global_store_dwordx4 v[194:195], v[230:233], off offset:64
	v_add_f32_e32 v226, v4, v218
	v_add_f32_e32 v227, v5, v219
	v_add_f32_e32 v228, v6, v220
	v_add_f32_e32 v229, v7, v221
	v_mul_f32_e32 v226, 0xbfb8aa3b, v226
	v_mul_f32_e32 v227, 0xbfb8aa3b, v227
	v_mul_f32_e32 v228, 0xbfb8aa3b, v228
	v_mul_f32_e32 v229, 0xbfb8aa3b, v229
	v_exp_f32_e32 v226, v226
	v_exp_f32_e32 v227, v227
	v_exp_f32_e32 v228, v228
	v_exp_f32_e32 v229, v229
	v_add_f32_e32 v226, 1.0, v226
	v_add_f32_e32 v227, 1.0, v227
	v_add_f32_e32 v228, 1.0, v228
	v_add_f32_e32 v229, 1.0, v229
	v_div_scale_f32 v134, s[2:3], v226, v226, 1.0
	v_div_scale_f32 v139, s[2:3], v227, v227, 1.0
	v_rcp_f32_e32 v135, v134
	v_rcp_f32_e32 v140, v139
	v_fma_f32 v136, -v134, v135, 1.0
	v_fma_f32 v141, -v139, v140, 1.0
	v_fmac_f32_e32 v135, v136, v135
	v_fmac_f32_e32 v140, v141, v140
	v_div_scale_f32 v137, vcc, 1.0, v226, 1.0
	v_mul_f32_e32 v138, v137, v135
	v_fma_f32 v136, -v134, v138, v137
	v_fmac_f32_e32 v138, v136, v135
	v_fma_f32 v134, -v134, v138, v137
	v_div_fmas_f32 v134, v134, v135, v138
	v_div_fixup_f32 v226, v134, v226, 1.0
	v_div_scale_f32 v165, vcc, 1.0, v227, 1.0
	v_mul_f32_e32 v166, v165, v140
	v_fma_f32 v141, -v139, v166, v165
	v_fmac_f32_e32 v166, v141, v140
	v_fma_f32 v139, -v139, v166, v165
	v_div_fmas_f32 v139, v139, v140, v166
	v_div_fixup_f32 v227, v139, v227, 1.0
	v_div_scale_f32 v134, s[2:3], v228, v228, 1.0
	v_div_scale_f32 v139, s[2:3], v229, v229, 1.0
	v_rcp_f32_e32 v135, v134
	v_rcp_f32_e32 v140, v139
	v_fma_f32 v136, -v134, v135, 1.0
	v_fma_f32 v141, -v139, v140, 1.0
	v_fmac_f32_e32 v135, v136, v135
	v_fmac_f32_e32 v140, v141, v140
	v_div_scale_f32 v137, vcc, 1.0, v228, 1.0
	v_mul_f32_e32 v138, v137, v135
	v_fma_f32 v136, -v134, v138, v137
	v_fmac_f32_e32 v138, v136, v135
	v_fma_f32 v134, -v134, v138, v137
	v_div_fmas_f32 v134, v134, v135, v138
	v_div_fixup_f32 v228, v134, v228, 1.0
	v_div_scale_f32 v165, vcc, 1.0, v229, 1.0
	v_mul_f32_e32 v166, v165, v140
	v_fma_f32 v141, -v139, v166, v165
	v_fmac_f32_e32 v166, v141, v140
	v_fma_f32 v139, -v139, v166, v165
	v_div_fmas_f32 v139, v139, v140, v166
	v_div_fixup_f32 v229, v139, v229, 1.0
	global_store_dwordx4 v[194:195], v[226:229], off offset:512
	v_add_f32_e32 v230, v0, v222
	v_add_f32_e32 v231, v1, v223
	v_add_f32_e32 v232, v2, v224
	v_add_f32_e32 v233, v3, v225
	v_mul_f32_e32 v230, 0xbfb8aa3b, v230
	v_mul_f32_e32 v231, 0xbfb8aa3b, v231
	v_mul_f32_e32 v232, 0xbfb8aa3b, v232
	v_mul_f32_e32 v233, 0xbfb8aa3b, v233
	v_exp_f32_e32 v230, v230
	v_exp_f32_e32 v231, v231
	v_exp_f32_e32 v232, v232
	v_exp_f32_e32 v233, v233
	v_add_f32_e32 v230, 1.0, v230
	v_add_f32_e32 v231, 1.0, v231
	v_add_f32_e32 v232, 1.0, v232
	v_add_f32_e32 v233, 1.0, v233
	v_div_scale_f32 v134, s[2:3], v230, v230, 1.0
	v_div_scale_f32 v139, s[2:3], v231, v231, 1.0
	v_rcp_f32_e32 v135, v134
	v_rcp_f32_e32 v140, v139
	v_fma_f32 v136, -v134, v135, 1.0
	v_fma_f32 v141, -v139, v140, 1.0
	v_fmac_f32_e32 v135, v136, v135
	v_fmac_f32_e32 v140, v141, v140
	v_div_scale_f32 v137, vcc, 1.0, v230, 1.0
	v_mul_f32_e32 v138, v137, v135
	v_fma_f32 v136, -v134, v138, v137
	v_fmac_f32_e32 v138, v136, v135
	v_fma_f32 v134, -v134, v138, v137
	v_div_fmas_f32 v134, v134, v135, v138
	v_div_fixup_f32 v230, v134, v230, 1.0
	v_div_scale_f32 v165, vcc, 1.0, v231, 1.0
	v_mul_f32_e32 v166, v165, v140
	v_fma_f32 v141, -v139, v166, v165
	v_fmac_f32_e32 v166, v141, v140
	v_fma_f32 v139, -v139, v166, v165
	v_div_fmas_f32 v139, v139, v140, v166
	v_div_fixup_f32 v231, v139, v231, 1.0
	v_div_scale_f32 v134, s[2:3], v232, v232, 1.0
	v_div_scale_f32 v139, s[2:3], v233, v233, 1.0
	v_rcp_f32_e32 v135, v134
	v_rcp_f32_e32 v140, v139
	v_fma_f32 v136, -v134, v135, 1.0
	v_fma_f32 v141, -v139, v140, 1.0
	v_fmac_f32_e32 v135, v136, v135
	v_fmac_f32_e32 v140, v141, v140
	v_div_scale_f32 v137, vcc, 1.0, v232, 1.0
	v_mul_f32_e32 v138, v137, v135
	v_fma_f32 v136, -v134, v138, v137
	v_fmac_f32_e32 v138, v136, v135
	v_fma_f32 v134, -v134, v138, v137
	v_div_fmas_f32 v134, v134, v135, v138
	v_div_fixup_f32 v232, v134, v232, 1.0
	v_div_scale_f32 v165, vcc, 1.0, v233, 1.0
	v_mul_f32_e32 v166, v165, v140
	v_fma_f32 v141, -v139, v166, v165
	v_fmac_f32_e32 v166, v141, v140
	v_fma_f32 v139, -v139, v166, v165
	v_div_fmas_f32 v139, v139, v140, v166
	v_div_fixup_f32 v233, v139, v233, 1.0
	global_store_dwordx4 v[194:195], v[230:233], off offset:576
